# main GEMM K-loop: the mid-phase s_setprio 0 / s_setprio 1 pair between the two 16-MFMA halves of each compute phase removed (outer raise and drop kept)
# baseline (speedup 1.0000x reference)
.LBB0_1199:
	s_add_i32 s87, s86, 2
	s_add_u32 s30, s8, 0x80
	s_addc_u32 s31, s9, 0
	s_add_i32 s88, 16, 0x10000
	s_cmp_eq_u32 s57, s60
	s_cselect_b32 s31, s25, s31
	s_cselect_b32 s30, s24, s30
	v_add_u32_e32 v0, s88, v237
	s_cselect_b32 vcc_hi, s27, s85
	s_cselect_b32 vcc_lo, s26, s84
	s_add_i32 s89, 16, 0x14000
	ds_read_b128 v[132:135], v0
	ds_read_b128 v[136:139], v0 offset:1024
	ds_read_b128 v[152:155], v0 offset:2048
	ds_read_b128 v[156:159], v0 offset:3072
	v_add_u32_e32 v0, s89, v237
	ds_read_b128 v[160:163], v0
	ds_read_b128 v[164:167], v0 offset:1024
	ds_read_b128 v[168:171], v0 offset:2048
	ds_read_b128 v[172:175], v0 offset:3072
	v_lshl_add_u64 v[2:3], s[8:9], 0, v[150:151]
	s_add_i32 m0, s95, 0xc000
	ds_read_b128 v[176:179], v246
	ds_read_b128 v[180:183], v246 offset:1024
	ds_read_b128 v[184:187], v246 offset:2048
	ds_read_b128 v[188:191], v246 offset:3072
	ds_read_b128 v[192:195], v246 offset:4096
	ds_read_b128 v[196:199], v246 offset:5120
	ds_read_b128 v[200:203], v246 offset:6144
	ds_read_b128 v[204:207], v246 offset:7168
	global_load_lds_dwordx4 v[2:3], off
	v_lshl_add_u64 v[2:3], s[8:9], 0, v[148:149]
	s_add_i32 m0, s95, 0xe000
	s_nop 0
	global_load_lds_dwordx4 v[2:3], off
	s_waitcnt vmcnt(8)
	s_waitcnt lgkmcnt(0)
	s_barrier
	s_setprio 1
	s_waitcnt lgkmcnt(0)
	v_mfma_f32_16x16x32_bf16 v[128:131], v[132:135], v[176:179], v[128:131]
	v_mfma_f32_16x16x32_bf16 v[124:127], v[152:155], v[176:179], v[124:127]
	v_mfma_f32_16x16x32_bf16 v[112:115], v[132:135], v[184:187], v[112:115]
	v_mfma_f32_16x16x32_bf16 v[108:111], v[152:155], v[184:187], v[108:111]
	v_mfma_f32_16x16x32_bf16 v[96:99], v[132:135], v[192:195], v[96:99]
	v_mfma_f32_16x16x32_bf16 v[92:95], v[152:155], v[192:195], v[92:95]
	v_mfma_f32_16x16x32_bf16 v[80:83], v[132:135], v[200:203], v[80:83]
	v_mfma_f32_16x16x32_bf16 v[76:79], v[152:155], v[200:203], v[76:79]
	v_mfma_f32_16x16x32_bf16 v[128:131], v[136:139], v[180:183], v[128:131]
	v_mfma_f32_16x16x32_bf16 v[124:127], v[156:159], v[180:183], v[124:127]
	v_mfma_f32_16x16x32_bf16 v[112:115], v[136:139], v[188:191], v[112:115]
	v_mfma_f32_16x16x32_bf16 v[108:111], v[156:159], v[188:191], v[108:111]
	v_mfma_f32_16x16x32_bf16 v[96:99], v[136:139], v[196:199], v[96:99]
	v_mfma_f32_16x16x32_bf16 v[92:95], v[156:159], v[196:199], v[92:95]
	v_mfma_f32_16x16x32_bf16 v[80:83], v[136:139], v[204:207], v[80:83]
	v_mfma_f32_16x16x32_bf16 v[76:79], v[156:159], v[204:207], v[76:79]
	v_mfma_f32_16x16x32_bf16 v[120:123], v[160:163], v[176:179], v[120:123]
	v_mfma_f32_16x16x32_bf16 v[116:119], v[168:171], v[176:179], v[116:119]
	v_mfma_f32_16x16x32_bf16 v[104:107], v[160:163], v[184:187], v[104:107]
	v_mfma_f32_16x16x32_bf16 v[100:103], v[168:171], v[184:187], v[100:103]
	v_mfma_f32_16x16x32_bf16 v[88:91], v[160:163], v[192:195], v[88:91]
	v_mfma_f32_16x16x32_bf16 v[84:87], v[168:171], v[192:195], v[84:87]
	v_mfma_f32_16x16x32_bf16 v[72:75], v[160:163], v[200:203], v[72:75]
	v_mfma_f32_16x16x32_bf16 v[68:71], v[168:171], v[200:203], v[68:71]
	v_mfma_f32_16x16x32_bf16 v[120:123], v[164:167], v[180:183], v[120:123]
	v_mfma_f32_16x16x32_bf16 v[116:119], v[172:175], v[180:183], v[116:119]
	v_mfma_f32_16x16x32_bf16 v[104:107], v[164:167], v[188:191], v[104:107]
	v_mfma_f32_16x16x32_bf16 v[100:103], v[172:175], v[188:191], v[100:103]
	v_mfma_f32_16x16x32_bf16 v[88:91], v[164:167], v[196:199], v[88:91]
	v_mfma_f32_16x16x32_bf16 v[84:87], v[172:175], v[196:199], v[84:87]
	v_mfma_f32_16x16x32_bf16 v[72:75], v[164:167], v[204:207], v[72:75]
	v_mfma_f32_16x16x32_bf16 v[68:71], v[172:175], v[204:207], v[68:71]
	s_setprio 0
	s_barrier
	s_add_i32 s88, s88, s93
	v_lshl_add_u64 v[208:209], vcc, 0, v[142:143]
	s_mov_b32 m0, s88
	ds_read_b128 v[176:179], v246 offset:16384
	ds_read_b128 v[180:183], v246 offset:17408
	ds_read_b128 v[184:187], v246 offset:18432
	ds_read_b128 v[188:191], v246 offset:19456
	ds_read_b128 v[192:195], v246 offset:20480
	ds_read_b128 v[196:199], v246 offset:21504
	ds_read_b128 v[200:203], v246 offset:22528
	ds_read_b128 v[204:207], v246 offset:23552
	global_load_lds_dwordx4 v[208:209], off
	s_add_i32 m0, s88, 0x2000
	v_lshl_add_u64 v[210:211], vcc, 0, v[144:145]
	s_add_u32 vcc_lo, vcc_lo, s18
	s_addc_u32 vcc_hi, vcc_hi, 0
	s_add_i32 s88, s89, s93
	global_load_lds_dwordx4 v[210:211], off
	v_lshl_add_u64 v[212:213], vcc, 0, v[142:143]
	s_mov_b32 m0, s88
	v_lshl_add_u64 v[214:215], vcc, 0, v[144:145]
	global_load_lds_dwordx4 v[212:213], off
	s_add_i32 m0, s88, 0x2000
	v_lshl_add_u64 v[224:225], s[30:31], 0, v[142:143]
	global_load_lds_dwordx4 v[214:215], off
	s_mov_b32 m0, s95
	v_lshl_add_u64 v[226:227], s[30:31], 0, v[144:145]
	global_load_lds_dwordx4 v[224:225], off
	s_mov_b32 m0, s96
	s_nop 0
	global_load_lds_dwordx4 v[226:227], off
	s_waitcnt vmcnt(8)
	s_waitcnt lgkmcnt(0)
	s_barrier
	s_setprio 1
	s_waitcnt lgkmcnt(0)
	v_mfma_f32_16x16x32_bf16 v[64:67], v[132:135], v[176:179], v[64:67]
	v_mfma_f32_16x16x32_bf16 v[60:63], v[152:155], v[176:179], v[60:63]
	v_mfma_f32_16x16x32_bf16 v[48:51], v[132:135], v[184:187], v[48:51]
	v_mfma_f32_16x16x32_bf16 v[44:47], v[152:155], v[184:187], v[44:47]
	v_mfma_f32_16x16x32_bf16 v[32:35], v[132:135], v[192:195], v[32:35]
	v_mfma_f32_16x16x32_bf16 v[28:31], v[152:155], v[192:195], v[28:31]
	v_mfma_f32_16x16x32_bf16 v[16:19], v[132:135], v[200:203], v[16:19]
	v_mfma_f32_16x16x32_bf16 v[12:15], v[152:155], v[200:203], v[12:15]
	v_mfma_f32_16x16x32_bf16 v[64:67], v[136:139], v[180:183], v[64:67]
	v_mfma_f32_16x16x32_bf16 v[60:63], v[156:159], v[180:183], v[60:63]
	v_mfma_f32_16x16x32_bf16 v[48:51], v[136:139], v[188:191], v[48:51]
	v_mfma_f32_16x16x32_bf16 v[44:47], v[156:159], v[188:191], v[44:47]
	v_mfma_f32_16x16x32_bf16 v[32:35], v[136:139], v[196:199], v[32:35]
	v_mfma_f32_16x16x32_bf16 v[28:31], v[156:159], v[196:199], v[28:31]
	v_mfma_f32_16x16x32_bf16 v[16:19], v[136:139], v[204:207], v[16:19]
	v_mfma_f32_16x16x32_bf16 v[12:15], v[156:159], v[204:207], v[12:15]
	v_mfma_f32_16x16x32_bf16 v[56:59], v[160:163], v[176:179], v[56:59]
	v_mfma_f32_16x16x32_bf16 v[52:55], v[168:171], v[176:179], v[52:55]
	v_mfma_f32_16x16x32_bf16 v[40:43], v[160:163], v[184:187], v[40:43]
	v_mfma_f32_16x16x32_bf16 v[36:39], v[168:171], v[184:187], v[36:39]
	v_mfma_f32_16x16x32_bf16 v[24:27], v[160:163], v[192:195], v[24:27]
	v_mfma_f32_16x16x32_bf16 v[20:23], v[168:171], v[192:195], v[20:23]
	v_mfma_f32_16x16x32_bf16 v[8:11], v[160:163], v[200:203], v[8:11]
	v_mfma_f32_16x16x32_bf16 v[2:5], v[168:171], v[200:203], v[4:7]
	v_mfma_f32_16x16x32_bf16 v[56:59], v[164:167], v[180:183], v[56:59]
	v_mfma_f32_16x16x32_bf16 v[52:55], v[172:175], v[180:183], v[52:55]
	v_mfma_f32_16x16x32_bf16 v[40:43], v[164:167], v[188:191], v[40:43]
	v_mfma_f32_16x16x32_bf16 v[36:39], v[172:175], v[188:191], v[36:39]
	v_mfma_f32_16x16x32_bf16 v[24:27], v[164:167], v[196:199], v[24:27]
	v_mfma_f32_16x16x32_bf16 v[20:23], v[172:175], v[196:199], v[20:23]
	v_mfma_f32_16x16x32_bf16 v[8:11], v[164:167], v[204:207], v[8:11]
	v_mfma_f32_16x16x32_bf16 v[2:5], v[172:175], v[204:207], v[2:5]
	s_setprio 0
	s_barrier
	s_add_i32 s88, 16, 0x18000
	v_add_u32_e32 v0, s88, v237
	s_add_i32 s89, 16, 0x1c000
	ds_read_b128 v[132:135], v0
	ds_read_b128 v[136:139], v0 offset:1024
	ds_read_b128 v[152:155], v0 offset:2048
	ds_read_b128 v[156:159], v0 offset:3072
	v_add_u32_e32 v0, s89, v237
	ds_read_b128 v[160:163], v0
	ds_read_b128 v[164:167], v0 offset:1024
	ds_read_b128 v[168:171], v0 offset:2048
	ds_read_b128 v[172:175], v0 offset:3072
	s_add_u32 s30, s30, s18
	s_addc_u32 s31, s31, 0
	s_mov_b32 m0, s97
	v_lshl_add_u64 v[6:7], s[30:31], 0, v[142:143]
	ds_read_b128 v[176:179], v246 offset:32768
	ds_read_b128 v[180:183], v246 offset:33792
	ds_read_b128 v[184:187], v246 offset:34816
	ds_read_b128 v[188:191], v246 offset:35840
	ds_read_b128 v[192:195], v246 offset:36864
	ds_read_b128 v[196:199], v246 offset:37888
	ds_read_b128 v[200:203], v246 offset:38912
	ds_read_b128 v[204:207], v246 offset:39936
	global_load_lds_dwordx4 v[6:7], off
	v_lshl_add_u64 v[6:7], s[30:31], 0, v[144:145]
	s_mov_b32 m0, s58
	s_nop 0
	global_load_lds_dwordx4 v[6:7], off
	s_waitcnt vmcnt(8)
	s_waitcnt lgkmcnt(0)
	s_barrier
	s_setprio 1
	s_waitcnt lgkmcnt(0)
	v_mfma_f32_16x16x32_bf16 v[128:131], v[132:135], v[176:179], v[128:131]
	v_mfma_f32_16x16x32_bf16 v[124:127], v[152:155], v[176:179], v[124:127]
	v_mfma_f32_16x16x32_bf16 v[112:115], v[132:135], v[184:187], v[112:115]
	v_mfma_f32_16x16x32_bf16 v[108:111], v[152:155], v[184:187], v[108:111]
	v_mfma_f32_16x16x32_bf16 v[96:99], v[132:135], v[192:195], v[96:99]
	v_mfma_f32_16x16x32_bf16 v[92:95], v[152:155], v[192:195], v[92:95]
	v_mfma_f32_16x16x32_bf16 v[80:83], v[132:135], v[200:203], v[80:83]
	v_mfma_f32_16x16x32_bf16 v[76:79], v[152:155], v[200:203], v[76:79]
	v_mfma_f32_16x16x32_bf16 v[128:131], v[136:139], v[180:183], v[128:131]
	v_mfma_f32_16x16x32_bf16 v[124:127], v[156:159], v[180:183], v[124:127]
	v_mfma_f32_16x16x32_bf16 v[112:115], v[136:139], v[188:191], v[112:115]
	v_mfma_f32_16x16x32_bf16 v[108:111], v[156:159], v[188:191], v[108:111]
	v_mfma_f32_16x16x32_bf16 v[96:99], v[136:139], v[196:199], v[96:99]
	v_mfma_f32_16x16x32_bf16 v[92:95], v[156:159], v[196:199], v[92:95]
	v_mfma_f32_16x16x32_bf16 v[80:83], v[136:139], v[204:207], v[80:83]
	v_mfma_f32_16x16x32_bf16 v[76:79], v[156:159], v[204:207], v[76:79]
	v_mfma_f32_16x16x32_bf16 v[120:123], v[160:163], v[176:179], v[120:123]
	v_mfma_f32_16x16x32_bf16 v[116:119], v[168:171], v[176:179], v[116:119]
	v_mfma_f32_16x16x32_bf16 v[104:107], v[160:163], v[184:187], v[104:107]
	v_mfma_f32_16x16x32_bf16 v[100:103], v[168:171], v[184:187], v[100:103]
	v_mfma_f32_16x16x32_bf16 v[88:91], v[160:163], v[192:195], v[88:91]
	v_mfma_f32_16x16x32_bf16 v[84:87], v[168:171], v[192:195], v[84:87]
	v_mfma_f32_16x16x32_bf16 v[72:75], v[160:163], v[200:203], v[72:75]
	v_mfma_f32_16x16x32_bf16 v[68:71], v[168:171], v[200:203], v[68:71]
	v_mfma_f32_16x16x32_bf16 v[120:123], v[164:167], v[180:183], v[120:123]
	v_mfma_f32_16x16x32_bf16 v[116:119], v[172:175], v[180:183], v[116:119]
	v_mfma_f32_16x16x32_bf16 v[104:107], v[164:167], v[188:191], v[104:107]
	v_mfma_f32_16x16x32_bf16 v[100:103], v[172:175], v[188:191], v[100:103]
	v_mfma_f32_16x16x32_bf16 v[88:91], v[164:167], v[196:199], v[88:91]
	v_mfma_f32_16x16x32_bf16 v[84:87], v[172:175], v[196:199], v[84:87]
	v_mfma_f32_16x16x32_bf16 v[72:75], v[164:167], v[204:207], v[72:75]
	v_mfma_f32_16x16x32_bf16 v[68:71], v[172:175], v[204:207], v[68:71]
	s_setprio 0
	s_barrier
	s_add_i32 s30, s88, s93
	v_lshl_add_u64 v[6:7], v[208:209], 0, s[36:37]
	s_mov_b32 m0, s30
	ds_read_b128 v[176:179], v246 offset:49152
	ds_read_b128 v[180:183], v246 offset:50176
	ds_read_b128 v[184:187], v246 offset:51200
	ds_read_b128 v[188:191], v246 offset:52224
	ds_read_b128 v[192:195], v246 offset:53248
	ds_read_b128 v[196:199], v246 offset:54272
	ds_read_b128 v[200:203], v246 offset:55296
	ds_read_b128 v[204:207], v246 offset:56320
	global_load_lds_dwordx4 v[6:7], off
	v_lshl_add_u64 v[6:7], v[210:211], 0, s[36:37]
	s_add_i32 m0, s30, 0x2000
	s_add_i32 s30, s89, s93
	global_load_lds_dwordx4 v[6:7], off
	v_lshl_add_u64 v[6:7], v[212:213], 0, s[36:37]
	s_mov_b32 m0, s30
	s_nop 0
	global_load_lds_dwordx4 v[6:7], off
	v_lshl_add_u64 v[6:7], v[214:215], 0, s[36:37]
	s_add_i32 m0, s30, 0x2000
	s_nop 0
	global_load_lds_dwordx4 v[6:7], off
	v_lshl_add_u64 v[6:7], v[224:225], 0, s[36:37]
	s_mov_b32 m0, s21
	s_nop 0
	global_load_lds_dwordx4 v[6:7], off
	v_lshl_add_u64 v[6:7], v[226:227], 0, s[36:37]
	s_mov_b32 m0, s33
	s_nop 0
	global_load_lds_dwordx4 v[6:7], off
	s_waitcnt vmcnt(8)
	s_waitcnt lgkmcnt(0)
	s_barrier
	s_setprio 1
	s_waitcnt lgkmcnt(0)
	v_mfma_f32_16x16x32_bf16 v[64:67], v[132:135], v[176:179], v[64:67]
	v_mfma_f32_16x16x32_bf16 v[60:63], v[152:155], v[176:179], v[60:63]
	v_mfma_f32_16x16x32_bf16 v[48:51], v[132:135], v[184:187], v[48:51]
	v_mfma_f32_16x16x32_bf16 v[44:47], v[152:155], v[184:187], v[44:47]
	v_mfma_f32_16x16x32_bf16 v[32:35], v[132:135], v[192:195], v[32:35]
	v_mfma_f32_16x16x32_bf16 v[28:31], v[152:155], v[192:195], v[28:31]
	v_mfma_f32_16x16x32_bf16 v[16:19], v[132:135], v[200:203], v[16:19]
	v_mfma_f32_16x16x32_bf16 v[12:15], v[152:155], v[200:203], v[12:15]
	v_mfma_f32_16x16x32_bf16 v[64:67], v[136:139], v[180:183], v[64:67]
	v_mfma_f32_16x16x32_bf16 v[60:63], v[156:159], v[180:183], v[60:63]
	v_mfma_f32_16x16x32_bf16 v[48:51], v[136:139], v[188:191], v[48:51]
	v_mfma_f32_16x16x32_bf16 v[44:47], v[156:159], v[188:191], v[44:47]
	v_mfma_f32_16x16x32_bf16 v[32:35], v[136:139], v[196:199], v[32:35]
	v_mfma_f32_16x16x32_bf16 v[28:31], v[156:159], v[196:199], v[28:31]
	v_mfma_f32_16x16x32_bf16 v[16:19], v[136:139], v[204:207], v[16:19]
	v_mfma_f32_16x16x32_bf16 v[12:15], v[156:159], v[204:207], v[12:15]
	v_mfma_f32_16x16x32_bf16 v[56:59], v[160:163], v[176:179], v[56:59]
	v_mfma_f32_16x16x32_bf16 v[52:55], v[168:171], v[176:179], v[52:55]
	v_mfma_f32_16x16x32_bf16 v[40:43], v[160:163], v[184:187], v[40:43]
	v_mfma_f32_16x16x32_bf16 v[36:39], v[168:171], v[184:187], v[36:39]
	v_mfma_f32_16x16x32_bf16 v[24:27], v[160:163], v[192:195], v[24:27]
	v_mfma_f32_16x16x32_bf16 v[20:23], v[168:171], v[192:195], v[20:23]
	v_mfma_f32_16x16x32_bf16 v[6:9], v[160:163], v[200:203], v[8:11]
	v_mfma_f32_16x16x32_bf16 v[2:5], v[168:171], v[200:203], v[2:5]
	v_mfma_f32_16x16x32_bf16 v[56:59], v[164:167], v[180:183], v[56:59]
	v_mfma_f32_16x16x32_bf16 v[52:55], v[172:175], v[180:183], v[52:55]
	v_mfma_f32_16x16x32_bf16 v[40:43], v[164:167], v[188:191], v[40:43]
	v_mfma_f32_16x16x32_bf16 v[36:39], v[172:175], v[188:191], v[36:39]
	v_mfma_f32_16x16x32_bf16 v[24:27], v[164:167], v[196:199], v[24:27]
	v_mfma_f32_16x16x32_bf16 v[20:23], v[172:175], v[196:199], v[20:23]
	v_mfma_f32_16x16x32_bf16 v[8:11], v[164:167], v[204:207], v[6:9]
	v_mfma_f32_16x16x32_bf16 v[4:7], v[172:175], v[204:207], v[2:5]
	s_setprio 0
	s_barrier
	s_andn2_b64 vcc, exec, s[22:23]
	s_cbranch_vccnz .LBB0_1202
	s_bitcmp1_b32 s86, 1
	s_cselect_b64 s[30:31], -1, 0
	s_cmp_lt_u32 s87, s56
	s_cselect_b64 vcc, -1, 0
	s_and_b64 s[30:31], s[30:31], vcc
	s_andn2_b64 vcc, exec, s[30:31]
	s_cbranch_vccnz .LBB0_1202
	v_mov_b32_e32 v140, v234
	v_mov_b32_e32 v0, v235
	s_nop 0
	v_lshl_add_u32 v0, v0, 2, s4
	v_add_u32_e32 v2, s52, v0
	v_ashrrev_i32_e32 v3, 31, v2
	v_lshl_add_u64 v[136:137], v[2:3], 2, s[6:7]
	v_add_u32_e32 v174, s0, v140
	v_lshlrev_b64 v[2:3], 1, v[2:3]
	v_mad_i64_i32 v[152:153], s[30:31], v174, s2, v[2:3]
	s_add_u32 s30, s10, s60
	s_addc_u32 s31, s11, s61
	v_lshl_add_u64 v[152:153], s[30:31], 0, v[152:153]
	v_add_co_u32_e32 v154, vcc, s76, v152
	v_add_u32_e32 v175, 16, v174
	s_nop 0
	v_addc_co_u32_e32 v155, vcc, 0, v153, vcc
	v_add_co_u32_e32 v152, vcc, s77, v152
	global_load_dwordx4 v[132:135], v[136:137], off offset:-4096
	s_nop 0
	global_load_dwordx4 v[136:139], v[136:137], off
	v_addc_co_u32_e32 v153, vcc, 0, v153, vcc
	v_mad_i64_i32 v[156:157], vcc, v175, s2, v[2:3]
	v_lshl_add_u64 v[156:157], s[30:31], 0, v[156:157]
	v_add_co_u32_e32 v158, vcc, s76, v156
	v_add_u32_e32 v176, 32, v174
	s_nop 0
	v_addc_co_u32_e32 v159, vcc, 0, v157, vcc
	v_add_co_u32_e32 v156, vcc, s77, v156
	v_add_u32_e32 v177, 48, v174
	s_nop 0
	v_addc_co_u32_e32 v157, vcc, 0, v157, vcc
	global_load_dwordx2 v[182:183], v[154:155], off offset:3072
	global_load_dwordx2 v[184:185], v[152:153], off offset:1024
	global_load_dwordx2 v[186:187], v[158:159], off offset:3072
	global_load_dwordx2 v[188:189], v[156:157], off offset:1024
	v_mad_i64_i32 v[152:153], vcc, v176, s2, v[2:3]
	v_lshl_add_u64 v[152:153], s[30:31], 0, v[152:153]
	v_add_co_u32_e32 v154, vcc, s76, v152
	v_add_u32_e32 v178, 0x80, v174
	s_nop 0
	v_addc_co_u32_e32 v155, vcc, 0, v153, vcc
	v_add_co_u32_e32 v152, vcc, s77, v152
	v_add_u32_e32 v179, 0x90, v174
	s_nop 0
	v_addc_co_u32_e32 v153, vcc, 0, v153, vcc
	v_mad_i64_i32 v[156:157], vcc, v177, s2, v[2:3]
	v_lshl_add_u64 v[156:157], s[30:31], 0, v[156:157]
	v_add_co_u32_e32 v158, vcc, s76, v156
	v_add_u32_e32 v180, 0xa0, v174
	s_nop 0
	v_addc_co_u32_e32 v159, vcc, 0, v157, vcc
	v_add_co_u32_e32 v156, vcc, s77, v156
	v_add_u32_e32 v181, 0xb0, v174
	s_nop 0
	v_addc_co_u32_e32 v157, vcc, 0, v157, vcc
	global_load_dwordx2 v[170:171], v[154:155], off offset:3072
	global_load_dwordx2 v[172:173], v[152:153], off offset:1024
	global_load_dwordx2 v[166:167], v[158:159], off offset:3072
	global_load_dwordx2 v[168:169], v[156:157], off offset:1024
	v_mad_i64_i32 v[152:153], vcc, v178, s2, v[2:3]
	v_lshl_add_u64 v[152:153], s[30:31], 0, v[152:153]
	v_add_co_u32_e32 v154, vcc, s76, v152
	s_nop 1
	v_addc_co_u32_e32 v155, vcc, 0, v153, vcc
	v_add_co_u32_e32 v152, vcc, s77, v152
	s_nop 1
	v_addc_co_u32_e32 v153, vcc, 0, v153, vcc
	v_mad_i64_i32 v[156:157], vcc, v179, s2, v[2:3]
	v_lshl_add_u64 v[156:157], s[30:31], 0, v[156:157]
	v_add_co_u32_e32 v158, vcc, s76, v156
	s_nop 1
	v_addc_co_u32_e32 v159, vcc, 0, v157, vcc
	v_add_co_u32_e32 v156, vcc, s77, v156
	s_nop 1
	v_addc_co_u32_e32 v157, vcc, 0, v157, vcc
	global_load_dwordx2 v[162:163], v[154:155], off offset:3072
	global_load_dwordx2 v[164:165], v[152:153], off offset:1024
	s_nop 0
	global_load_dwordx2 v[158:159], v[158:159], off offset:3072
	s_nop 0
	global_load_dwordx2 v[160:161], v[156:157], off offset:1024
	v_mad_i64_i32 v[152:153], vcc, v180, s2, v[2:3]
	v_lshl_add_u64 v[152:153], s[30:31], 0, v[152:153]
	v_add_co_u32_e32 v154, vcc, s76, v152
	s_nop 1
	v_addc_co_u32_e32 v155, vcc, 0, v153, vcc
	v_add_co_u32_e32 v152, vcc, s77, v152
	s_nop 1
	v_addc_co_u32_e32 v153, vcc, 0, v153, vcc
	v_mad_i64_i32 v[2:3], vcc, v181, s2, v[2:3]
	v_lshl_add_u64 v[2:3], s[30:31], 0, v[2:3]
	v_add_co_u32_e32 v190, vcc, s76, v2
	s_nop 1
	v_addc_co_u32_e32 v191, vcc, 0, v3, vcc
	v_add_co_u32_e32 v192, vcc, s77, v2
	s_waitcnt vmcnt(0)
	v_lshlrev_b32_e32 v2, 16, v184
	v_add_f32_e32 v2, v136, v2
	v_mul_f32_e32 v2, 0xbfb8aa3b, v2
	v_exp_f32_e32 v140, v2
	v_lshlrev_b32_e32 v2, 16, v182
	v_add_f32_e32 v2, v132, v2
	v_mul_f32_e32 v2, 0xbfb8aa3b, v2
	v_exp_f32_e32 v141, v2
	v_addc_co_u32_e32 v193, vcc, 0, v3, vcc
	global_load_dwordx2 v[154:155], v[154:155], off offset:3072
	s_nop 0
	global_load_dwordx2 v[156:157], v[152:153], off offset:1024
	global_load_dwordx2 v[2:3], v[190:191], off offset:3072
	s_nop 0
	global_load_dwordx2 v[152:153], v[192:193], off offset:1024
	v_min_f32_e32 v190, 0x60ad78ec, v140
	v_min_f32_e32 v140, 0x60ad78ec, v141
	v_and_b32_e32 v141, 0xffff0000, v184
	v_add_f32_e32 v141, v137, v141
	v_mul_f32_e32 v141, 0xbfb8aa3b, v141
	v_exp_f32_e32 v141, v141
	v_and_b32_e32 v182, 0xffff0000, v182
	v_add_f32_e32 v182, v133, v182
	v_mul_f32_e32 v182, 0xbfb8aa3b, v182
	v_exp_f32_e32 v182, v182
	v_min_f32_e32 v191, 0x60ad78ec, v141
	v_lshlrev_b32_e32 v141, 16, v185
	v_add_f32_e32 v141, v138, v141
	v_add_f32_e32 v140, 1.0, v140
	v_mul_f32_e32 v141, 0xbfb8aa3b, v141
	v_rcp_f32_e32 v192, v140
	v_min_f32_e32 v140, 0x60ad78ec, v182
	v_exp_f32_e32 v141, v141
	v_lshlrev_b32_e32 v182, 16, v183
	v_add_f32_e32 v182, v134, v182
	v_mul_f32_e32 v182, 0xbfb8aa3b, v182
	v_and_b32_e32 v183, 0xffff0000, v183
	v_exp_f32_e32 v184, v182
	v_add_f32_e32 v183, v135, v183
	v_min_f32_e32 v182, 0x60ad78ec, v141
	v_and_b32_e32 v141, 0xffff0000, v185
	v_mul_f32_e32 v183, 0xbfb8aa3b, v183
	v_add_f32_e32 v141, v139, v141
	v_exp_f32_e32 v185, v183
	v_add_f32_e32 v140, 1.0, v140
	v_mul_f32_e32 v141, 0xbfb8aa3b, v141
	v_rcp_f32_e32 v193, v140
	v_min_f32_e32 v140, 0x60ad78ec, v184
	v_exp_f32_e32 v141, v141
	v_add_f32_e32 v140, 1.0, v140
	v_rcp_f32_e32 v184, v140
	v_min_f32_e32 v140, 0x60ad78ec, v185
	v_add_f32_e32 v140, 1.0, v140
	v_min_f32_e32 v183, 0x60ad78ec, v141
	v_rcp_f32_e32 v185, v140
	v_lshlrev_b32_e32 v140, 16, v188
	v_lshlrev_b32_e32 v141, 16, v186
	v_add_f32_e32 v140, v136, v140
	v_add_f32_e32 v141, v132, v141
	v_mul_f32_e32 v140, 0xbfb8aa3b, v140
	v_mul_f32_e32 v141, 0xbfb8aa3b, v141
	v_exp_f32_e32 v140, v140
	v_exp_f32_e32 v141, v141
	v_pk_add_f32 v[182:183], v[182:183], 1.0 op_sel_hi:[1,0]
	v_pk_add_f32 v[190:191], v[190:191], 1.0 op_sel_hi:[1,0]
	v_pk_mul_f32 v[182:183], v[182:183], v[184:185]
	v_pk_mul_f32 v[190:191], v[190:191], v[192:193]
	v_pk_mul_f32 v[130:131], v[130:131], v[182:183]
	v_min_f32_e32 v182, 0x60ad78ec, v140
	v_min_f32_e32 v140, 0x60ad78ec, v141
	v_and_b32_e32 v141, 0xffff0000, v188
	v_add_f32_e32 v141, v137, v141
	v_mul_f32_e32 v141, 0xbfb8aa3b, v141
	v_exp_f32_e32 v141, v141
	v_and_b32_e32 v183, 0xffff0000, v186
	v_add_f32_e32 v183, v133, v183
	v_mul_f32_e32 v183, 0xbfb8aa3b, v183
	v_exp_f32_e32 v185, v183
	v_min_f32_e32 v183, 0x60ad78ec, v141
	v_lshlrev_b32_e32 v141, 16, v189
	v_add_f32_e32 v141, v138, v141
	v_add_f32_e32 v140, 1.0, v140
	v_mul_f32_e32 v141, 0xbfb8aa3b, v141
	v_rcp_f32_e32 v184, v140
	v_min_f32_e32 v140, 0x60ad78ec, v185
	v_exp_f32_e32 v141, v141
	v_lshlrev_b32_e32 v185, 16, v187
	v_add_f32_e32 v185, v134, v185
	v_mul_f32_e32 v185, 0xbfb8aa3b, v185
	v_and_b32_e32 v187, 0xffff0000, v187
	v_exp_f32_e32 v188, v185
	v_add_f32_e32 v187, v135, v187
	v_min_f32_e32 v186, 0x60ad78ec, v141
	v_and_b32_e32 v141, 0xffff0000, v189
	v_mul_f32_e32 v187, 0xbfb8aa3b, v187
	v_add_f32_e32 v141, v139, v141
	v_exp_f32_e32 v189, v187
	v_add_f32_e32 v140, 1.0, v140
	v_mul_f32_e32 v141, 0xbfb8aa3b, v141
	v_rcp_f32_e32 v185, v140
	v_min_f32_e32 v140, 0x60ad78ec, v188
	v_exp_f32_e32 v141, v141
	v_add_f32_e32 v140, 1.0, v140
	v_rcp_f32_e32 v188, v140
	v_min_f32_e32 v140, 0x60ad78ec, v189
	v_add_f32_e32 v140, 1.0, v140
	v_min_f32_e32 v187, 0x60ad78ec, v141
	v_rcp_f32_e32 v189, v140
	v_lshlrev_b32_e32 v140, 16, v172
	v_lshlrev_b32_e32 v141, 16, v170
	v_add_f32_e32 v140, v136, v140
	v_add_f32_e32 v141, v132, v141
	v_mul_f32_e32 v140, 0xbfb8aa3b, v140
	v_mul_f32_e32 v141, 0xbfb8aa3b, v141
	v_exp_f32_e32 v140, v140
	v_exp_f32_e32 v141, v141
	v_pk_add_f32 v[182:183], v[182:183], 1.0 op_sel_hi:[1,0]
	v_and_b32_e32 v170, 0xffff0000, v170
	v_pk_mul_f32 v[182:183], v[182:183], v[184:185]
	v_add_f32_e32 v170, v133, v170
	v_pk_mul_f32 v[112:113], v[112:113], v[182:183]
	v_min_f32_e32 v182, 0x60ad78ec, v140
	v_min_f32_e32 v140, 0x60ad78ec, v141
	v_and_b32_e32 v141, 0xffff0000, v172
	v_add_f32_e32 v141, v137, v141
	v_mul_f32_e32 v141, 0xbfb8aa3b, v141
	v_exp_f32_e32 v141, v141
	v_mul_f32_e32 v170, 0xbfb8aa3b, v170
	v_exp_f32_e32 v170, v170
	v_pk_add_f32 v[186:187], v[186:187], 1.0 op_sel_hi:[1,0]
	v_min_f32_e32 v183, 0x60ad78ec, v141
	v_lshlrev_b32_e32 v141, 16, v173
	v_add_f32_e32 v141, v138, v141
	v_pk_mul_f32 v[184:185], v[186:187], v[188:189]
	v_add_f32_e32 v140, 1.0, v140
	v_mul_f32_e32 v141, 0xbfb8aa3b, v141
	v_pk_mul_f32 v[114:115], v[114:115], v[184:185]
	v_rcp_f32_e32 v184, v140
	v_min_f32_e32 v140, 0x60ad78ec, v170
	v_exp_f32_e32 v141, v141
	v_lshlrev_b32_e32 v170, 16, v171
	v_add_f32_e32 v170, v134, v170
	v_mul_f32_e32 v170, 0xbfb8aa3b, v170
	v_and_b32_e32 v171, 0xffff0000, v171
	v_exp_f32_e32 v172, v170
	v_add_f32_e32 v171, v135, v171
	v_min_f32_e32 v170, 0x60ad78ec, v141
	v_and_b32_e32 v141, 0xffff0000, v173
	v_mul_f32_e32 v171, 0xbfb8aa3b, v171
	v_add_f32_e32 v141, v139, v141
	v_exp_f32_e32 v173, v171
	v_add_f32_e32 v140, 1.0, v140
	v_mul_f32_e32 v141, 0xbfb8aa3b, v141
	v_rcp_f32_e32 v185, v140
	v_min_f32_e32 v140, 0x60ad78ec, v172
	v_exp_f32_e32 v141, v141
	v_add_f32_e32 v140, 1.0, v140
	v_rcp_f32_e32 v172, v140
	v_min_f32_e32 v140, 0x60ad78ec, v173
	v_add_f32_e32 v140, 1.0, v140
	v_min_f32_e32 v171, 0x60ad78ec, v141
	v_rcp_f32_e32 v173, v140
	v_lshlrev_b32_e32 v140, 16, v168
	v_lshlrev_b32_e32 v141, 16, v166
	v_add_f32_e32 v140, v136, v140
	v_add_f32_e32 v141, v132, v141
	v_mul_f32_e32 v140, 0xbfb8aa3b, v140
	v_mul_f32_e32 v141, 0xbfb8aa3b, v141
	v_exp_f32_e32 v140, v140
	v_exp_f32_e32 v141, v141
	v_pk_add_f32 v[170:171], v[170:171], 1.0 op_sel_hi:[1,0]
	v_and_b32_e32 v166, 0xffff0000, v166
	v_pk_mul_f32 v[170:171], v[170:171], v[172:173]
	v_add_f32_e32 v166, v133, v166
	v_pk_mul_f32 v[98:99], v[98:99], v[170:171]
	v_min_f32_e32 v170, 0x60ad78ec, v140
	v_min_f32_e32 v140, 0x60ad78ec, v141
	v_and_b32_e32 v141, 0xffff0000, v168
	v_add_f32_e32 v141, v137, v141
	v_mul_f32_e32 v141, 0xbfb8aa3b, v141
	v_exp_f32_e32 v141, v141
	v_mul_f32_e32 v166, 0xbfb8aa3b, v166
	v_exp_f32_e32 v166, v166
	v_add_f32_e32 v140, 1.0, v140
	v_min_f32_e32 v171, 0x60ad78ec, v141
	v_lshlrev_b32_e32 v141, 16, v169
	v_add_f32_e32 v141, v138, v141
	v_mul_f32_e32 v141, 0xbfb8aa3b, v141
	v_rcp_f32_e32 v172, v140
	v_min_f32_e32 v140, 0x60ad78ec, v166
	v_exp_f32_e32 v141, v141
	v_lshlrev_b32_e32 v166, 16, v167
	v_add_f32_e32 v166, v134, v166
	v_mul_f32_e32 v166, 0xbfb8aa3b, v166
	v_and_b32_e32 v167, 0xffff0000, v167
	v_exp_f32_e32 v168, v166
	v_add_f32_e32 v167, v135, v167
	v_min_f32_e32 v166, 0x60ad78ec, v141
	v_and_b32_e32 v141, 0xffff0000, v169
	v_mul_f32_e32 v167, 0xbfb8aa3b, v167
	v_add_f32_e32 v141, v139, v141
	v_exp_f32_e32 v169, v167
	v_add_f32_e32 v140, 1.0, v140
	v_mul_f32_e32 v141, 0xbfb8aa3b, v141
	v_rcp_f32_e32 v173, v140
	v_min_f32_e32 v140, 0x60ad78ec, v168
	v_exp_f32_e32 v141, v141
	v_add_f32_e32 v140, 1.0, v140
	v_rcp_f32_e32 v168, v140
	v_min_f32_e32 v140, 0x60ad78ec, v169
	v_add_f32_e32 v140, 1.0, v140
	v_min_f32_e32 v167, 0x60ad78ec, v141
	v_rcp_f32_e32 v169, v140
	v_lshlrev_b32_e32 v140, 16, v164
	v_lshlrev_b32_e32 v141, 16, v162
	v_add_f32_e32 v140, v136, v140
	v_add_f32_e32 v141, v132, v141
	v_mul_f32_e32 v140, 0xbfb8aa3b, v140
	v_mul_f32_e32 v141, 0xbfb8aa3b, v141
	v_exp_f32_e32 v140, v140
	v_exp_f32_e32 v141, v141
	v_pk_add_f32 v[166:167], v[166:167], 1.0 op_sel_hi:[1,0]
	v_and_b32_e32 v162, 0xffff0000, v162
	v_pk_mul_f32 v[166:167], v[166:167], v[168:169]
	v_add_f32_e32 v162, v133, v162
	v_pk_mul_f32 v[82:83], v[82:83], v[166:167]
	v_min_f32_e32 v166, 0x60ad78ec, v140
	v_min_f32_e32 v140, 0x60ad78ec, v141
	v_and_b32_e32 v141, 0xffff0000, v164
	v_add_f32_e32 v141, v137, v141
	v_mul_f32_e32 v141, 0xbfb8aa3b, v141
	v_exp_f32_e32 v141, v141
	v_mul_f32_e32 v162, 0xbfb8aa3b, v162
	v_exp_f32_e32 v162, v162
	v_add_f32_e32 v140, 1.0, v140
	v_min_f32_e32 v167, 0x60ad78ec, v141
	v_lshlrev_b32_e32 v141, 16, v165
	v_add_f32_e32 v141, v138, v141
	v_mul_f32_e32 v141, 0xbfb8aa3b, v141
	v_rcp_f32_e32 v168, v140
	v_min_f32_e32 v140, 0x60ad78ec, v162
	v_exp_f32_e32 v141, v141
	v_lshlrev_b32_e32 v162, 16, v163
	v_add_f32_e32 v162, v134, v162
	v_mul_f32_e32 v162, 0xbfb8aa3b, v162
	v_and_b32_e32 v163, 0xffff0000, v163
	v_exp_f32_e32 v164, v162
	v_add_f32_e32 v163, v135, v163
	v_min_f32_e32 v162, 0x60ad78ec, v141
	v_and_b32_e32 v141, 0xffff0000, v165
	v_mul_f32_e32 v163, 0xbfb8aa3b, v163
	v_add_f32_e32 v141, v139, v141
	v_exp_f32_e32 v165, v163
	v_add_f32_e32 v140, 1.0, v140
	v_mul_f32_e32 v141, 0xbfb8aa3b, v141
	v_rcp_f32_e32 v169, v140
	v_min_f32_e32 v140, 0x60ad78ec, v164
	v_exp_f32_e32 v141, v141
	v_add_f32_e32 v140, 1.0, v140
	v_rcp_f32_e32 v164, v140
	v_min_f32_e32 v140, 0x60ad78ec, v165
	v_add_f32_e32 v140, 1.0, v140
	v_min_f32_e32 v163, 0x60ad78ec, v141
	v_rcp_f32_e32 v165, v140
	v_lshlrev_b32_e32 v140, 16, v160
	v_lshlrev_b32_e32 v141, 16, v158
	v_add_f32_e32 v140, v136, v140
	v_add_f32_e32 v141, v132, v141
	v_mul_f32_e32 v140, 0xbfb8aa3b, v140
	v_mul_f32_e32 v141, 0xbfb8aa3b, v141
	v_exp_f32_e32 v140, v140
	v_exp_f32_e32 v141, v141
	v_pk_add_f32 v[162:163], v[162:163], 1.0 op_sel_hi:[1,0]
	v_and_b32_e32 v158, 0xffff0000, v158
	v_pk_mul_f32 v[162:163], v[162:163], v[164:165]
	v_add_f32_e32 v158, v133, v158
	v_pk_mul_f32 v[66:67], v[66:67], v[162:163]
	v_min_f32_e32 v162, 0x60ad78ec, v140
	v_min_f32_e32 v140, 0x60ad78ec, v141
	v_and_b32_e32 v141, 0xffff0000, v160
	v_add_f32_e32 v141, v137, v141
	v_mul_f32_e32 v141, 0xbfb8aa3b, v141
	v_exp_f32_e32 v141, v141
	v_mul_f32_e32 v158, 0xbfb8aa3b, v158
	v_exp_f32_e32 v158, v158
	v_add_f32_e32 v140, 1.0, v140
	v_min_f32_e32 v163, 0x60ad78ec, v141
	v_lshlrev_b32_e32 v141, 16, v161
	v_add_f32_e32 v141, v138, v141
	v_mul_f32_e32 v141, 0xbfb8aa3b, v141
	v_rcp_f32_e32 v164, v140
	v_min_f32_e32 v140, 0x60ad78ec, v158
	v_exp_f32_e32 v141, v141
	v_lshlrev_b32_e32 v158, 16, v159
	v_add_f32_e32 v158, v134, v158
	v_mul_f32_e32 v158, 0xbfb8aa3b, v158
	v_and_b32_e32 v159, 0xffff0000, v159
	v_exp_f32_e32 v160, v158
	v_add_f32_e32 v159, v135, v159
	v_min_f32_e32 v158, 0x60ad78ec, v141
	v_and_b32_e32 v141, 0xffff0000, v161
	v_mul_f32_e32 v159, 0xbfb8aa3b, v159
	v_add_f32_e32 v141, v139, v141
	v_exp_f32_e32 v161, v159
	v_add_f32_e32 v140, 1.0, v140
	v_mul_f32_e32 v141, 0xbfb8aa3b, v141
	v_rcp_f32_e32 v165, v140
	v_min_f32_e32 v140, 0x60ad78ec, v160
	v_exp_f32_e32 v141, v141
	v_add_f32_e32 v140, 1.0, v140
	v_rcp_f32_e32 v160, v140
	v_min_f32_e32 v140, 0x60ad78ec, v161
	v_add_f32_e32 v140, 1.0, v140
	v_min_f32_e32 v159, 0x60ad78ec, v141
	v_rcp_f32_e32 v161, v140
	s_waitcnt vmcnt(2)
	v_lshlrev_b32_e32 v140, 16, v156
	v_lshlrev_b32_e32 v141, 16, v154
	v_add_f32_e32 v140, v136, v140
	v_add_f32_e32 v141, v132, v141
	v_mul_f32_e32 v140, 0xbfb8aa3b, v140
	v_mul_f32_e32 v141, 0xbfb8aa3b, v141
	v_exp_f32_e32 v140, v140
	v_exp_f32_e32 v141, v141
	v_pk_add_f32 v[158:159], v[158:159], 1.0 op_sel_hi:[1,0]
	v_and_b32_e32 v154, 0xffff0000, v154
	v_pk_mul_f32 v[158:159], v[158:159], v[160:161]
	v_add_f32_e32 v154, v133, v154
	v_pk_mul_f32 v[50:51], v[50:51], v[158:159]
	v_min_f32_e32 v158, 0x60ad78ec, v140
	v_min_f32_e32 v140, 0x60ad78ec, v141
	v_and_b32_e32 v141, 0xffff0000, v156
	v_add_f32_e32 v141, v137, v141
	v_mul_f32_e32 v141, 0xbfb8aa3b, v141
	v_exp_f32_e32 v141, v141
	v_mul_f32_e32 v154, 0xbfb8aa3b, v154
	v_exp_f32_e32 v154, v154
	v_add_f32_e32 v140, 1.0, v140
	v_min_f32_e32 v159, 0x60ad78ec, v141
	v_lshlrev_b32_e32 v141, 16, v157
	v_add_f32_e32 v141, v138, v141
	v_rcp_f32_e32 v160, v140
	v_min_f32_e32 v140, 0x60ad78ec, v154
	v_mul_f32_e32 v141, 0xbfb8aa3b, v141
	v_lshlrev_b32_e32 v154, 16, v155
	v_exp_f32_e32 v141, v141
	v_add_f32_e32 v154, v134, v154
	v_mul_f32_e32 v154, 0xbfb8aa3b, v154
	v_and_b32_e32 v155, 0xffff0000, v155
	v_exp_f32_e32 v156, v154
	v_add_f32_e32 v155, v135, v155
	v_mul_f32_e32 v155, 0xbfb8aa3b, v155
	v_min_f32_e32 v154, 0x60ad78ec, v141
	v_and_b32_e32 v141, 0xffff0000, v157
	v_exp_f32_e32 v157, v155
	v_add_f32_e32 v140, 1.0, v140
	v_rcp_f32_e32 v161, v140
	v_min_f32_e32 v140, 0x60ad78ec, v156
	v_add_f32_e32 v140, 1.0, v140
	v_rcp_f32_e32 v156, v140
	v_min_f32_e32 v140, 0x60ad78ec, v157
	v_add_f32_e32 v140, 1.0, v140
	v_rcp_f32_e32 v157, v140
	s_waitcnt vmcnt(0)
	v_lshlrev_b32_e32 v140, 16, v152
	v_add_f32_e32 v136, v136, v140
	v_lshlrev_b32_e32 v140, 16, v2
	v_add_f32_e32 v132, v132, v140
	v_mul_f32_e32 v136, 0xbfb8aa3b, v136
	v_mul_f32_e32 v132, 0xbfb8aa3b, v132
	v_exp_f32_e32 v136, v136
	v_exp_f32_e32 v140, v132
	v_and_b32_e32 v2, 0xffff0000, v2
	v_add_f32_e32 v2, v133, v2
	v_min_f32_e32 v132, 0x60ad78ec, v136
	v_min_f32_e32 v136, 0x60ad78ec, v140
	v_and_b32_e32 v140, 0xffff0000, v152
	v_add_f32_e32 v137, v137, v140
	v_mul_f32_e32 v137, 0xbfb8aa3b, v137
	v_exp_f32_e32 v137, v137
	v_add_f32_e32 v133, 1.0, v136
	v_mul_f32_e32 v2, 0xbfb8aa3b, v2
	v_rcp_f32_e32 v136, v133
	v_min_f32_e32 v133, 0x60ad78ec, v137
	v_lshlrev_b32_e32 v137, 16, v153
	v_exp_f32_e32 v2, v2
	v_add_f32_e32 v137, v138, v137
	v_mul_f32_e32 v137, 0xbfb8aa3b, v137
	v_exp_f32_e32 v138, v137
	v_lshlrev_b32_e32 v137, 16, v3
	v_and_b32_e32 v3, 0xffff0000, v3
	v_add_f32_e32 v134, v134, v137
	v_add_f32_e32 v3, v135, v3
	v_min_f32_e32 v2, 0x60ad78ec, v2
	v_mul_f32_e32 v134, 0xbfb8aa3b, v134
	v_mul_f32_e32 v3, 0xbfb8aa3b, v3
	v_exp_f32_e32 v134, v134
	v_add_f32_e32 v2, 1.0, v2
	v_exp_f32_e32 v135, v3
	v_rcp_f32_e32 v137, v2
	v_min_f32_e32 v2, 0x60ad78ec, v138
	v_and_b32_e32 v138, 0xffff0000, v153
	v_add_f32_e32 v138, v139, v138
	v_mul_f32_e32 v138, 0xbfb8aa3b, v138
	v_min_f32_e32 v134, 0x60ad78ec, v134
	v_exp_f32_e32 v138, v138
	v_min_f32_e32 v135, 0x60ad78ec, v135
	v_add_f32_e32 v141, v139, v141
	v_add_f32_e32 v3, 1.0, v134
	v_add_f32_e32 v135, 1.0, v135
	v_mul_f32_e32 v141, 0xbfb8aa3b, v141
	v_rcp_f32_e32 v134, v3
	v_rcp_f32_e32 v135, v135
	v_exp_f32_e32 v141, v141
	v_min_f32_e32 v3, 0x60ad78ec, v138
	v_pk_add_f32 v[2:3], v[2:3], 1.0 op_sel_hi:[1,0]
	v_pk_add_f32 v[132:133], v[132:133], 1.0 op_sel_hi:[1,0]
	v_pk_mul_f32 v[2:3], v[2:3], v[134:135]
	v_min_f32_e32 v155, 0x60ad78ec, v141
	v_pk_mul_f32 v[18:19], v[18:19], v[2:3]
	v_add_u32_e32 v2, s20, v0
	v_pk_add_f32 v[154:155], v[154:155], 1.0 op_sel_hi:[1,0]
	v_ashrrev_i32_e32 v3, 31, v2
	v_pk_mul_f32 v[154:155], v[154:155], v[156:157]
	v_pk_mul_f32 v[152:153], v[132:133], v[136:137]
	v_lshl_add_u64 v[136:137], v[2:3], 2, s[6:7]
	v_lshlrev_b64 v[2:3], 1, v[2:3]
	v_pk_mul_f32 v[34:35], v[34:35], v[154:155]
	v_mad_i64_i32 v[154:155], vcc, v174, s2, v[2:3]
	v_lshl_add_u64 v[154:155], s[30:31], 0, v[154:155]
	v_add_co_u32_e32 v156, vcc, s76, v154
	v_pk_add_f32 v[182:183], v[182:183], 1.0 op_sel_hi:[1,0]
	s_nop 0
	v_addc_co_u32_e32 v157, vcc, 0, v155, vcc
	v_add_co_u32_e32 v154, vcc, s77, v154
	v_pk_mul_f32 v[182:183], v[182:183], v[184:185]
	s_nop 0
	v_addc_co_u32_e32 v155, vcc, 0, v155, vcc
	v_pk_mul_f32 v[96:97], v[96:97], v[182:183]
	v_pk_add_f32 v[158:159], v[158:159], 1.0 op_sel_hi:[1,0]
	global_load_dwordx4 v[132:135], v[136:137], off offset:-4096
	s_nop 0
	global_load_dwordx4 v[136:139], v[136:137], off
	v_pk_mul_f32 v[158:159], v[158:159], v[160:161]
	global_load_dwordx2 v[182:183], v[154:155], off offset:1024
	v_mad_i64_i32 v[154:155], vcc, v175, s2, v[2:3]
	v_lshl_add_u64 v[154:155], s[30:31], 0, v[154:155]
	v_pk_mul_f32 v[32:33], v[32:33], v[158:159]
	v_add_co_u32_e32 v158, vcc, s76, v154
	v_pk_mul_f32 v[16:17], v[16:17], v[152:153]
	s_nop 0
	v_addc_co_u32_e32 v159, vcc, 0, v155, vcc
	v_add_co_u32_e32 v154, vcc, s77, v154
	v_pk_add_f32 v[170:171], v[170:171], 1.0 op_sel_hi:[1,0]
	s_nop 0
	v_addc_co_u32_e32 v155, vcc, 0, v155, vcc
	global_load_dwordx2 v[184:185], v[158:159], off offset:3072
	global_load_dwordx2 v[186:187], v[154:155], off offset:1024
	global_load_dwordx2 v[188:189], v[156:157], off offset:3072
	v_mad_i64_i32 v[152:153], vcc, v176, s2, v[2:3]
	v_lshl_add_u64 v[152:153], s[30:31], 0, v[152:153]
	v_add_co_u32_e32 v154, vcc, s76, v152
	v_pk_add_f32 v[166:167], v[166:167], 1.0 op_sel_hi:[1,0]
	s_nop 0
	v_addc_co_u32_e32 v155, vcc, 0, v153, vcc
	v_add_co_u32_e32 v152, vcc, s77, v152
	v_pk_mul_f32 v[170:171], v[170:171], v[172:173]
	s_nop 0
	v_addc_co_u32_e32 v153, vcc, 0, v153, vcc
	v_mad_i64_i32 v[156:157], vcc, v177, s2, v[2:3]
	v_lshl_add_u64 v[156:157], s[30:31], 0, v[156:157]
	v_add_co_u32_e32 v158, vcc, s76, v156
	v_pk_mul_f32 v[166:167], v[166:167], v[168:169]
	s_nop 0
	v_addc_co_u32_e32 v159, vcc, 0, v157, vcc
	v_add_co_u32_e32 v156, vcc, s77, v156
	v_pk_mul_f32 v[80:81], v[80:81], v[170:171]
	v_pk_mul_f32 v[64:65], v[64:65], v[166:167]
	v_addc_co_u32_e32 v157, vcc, 0, v157, vcc
	global_load_dwordx2 v[170:171], v[154:155], off offset:3072
	global_load_dwordx2 v[172:173], v[152:153], off offset:1024
	global_load_dwordx2 v[166:167], v[158:159], off offset:3072
	global_load_dwordx2 v[168:169], v[156:157], off offset:1024
	v_mad_i64_i32 v[152:153], vcc, v178, s2, v[2:3]
	v_lshl_add_u64 v[152:153], s[30:31], 0, v[152:153]
	v_add_co_u32_e32 v154, vcc, s76, v152
	v_pk_add_f32 v[162:163], v[162:163], 1.0 op_sel_hi:[1,0]
	s_nop 0
	v_addc_co_u32_e32 v155, vcc, 0, v153, vcc
	v_add_co_u32_e32 v152, vcc, s77, v152
	v_pk_mul_f32 v[162:163], v[162:163], v[164:165]
	s_nop 0
	v_addc_co_u32_e32 v153, vcc, 0, v153, vcc
	v_mad_i64_i32 v[156:157], vcc, v179, s2, v[2:3]
	v_lshl_add_u64 v[156:157], s[30:31], 0, v[156:157]
	v_add_co_u32_e32 v158, vcc, s76, v156
	v_pk_mul_f32 v[48:49], v[48:49], v[162:163]
	s_nop 0
	v_addc_co_u32_e32 v159, vcc, 0, v157, vcc
	v_add_co_u32_e32 v156, vcc, s77, v156
	v_pk_mul_f32 v[128:129], v[128:129], v[190:191]
	s_nop 0
	v_addc_co_u32_e32 v157, vcc, 0, v157, vcc
	global_load_dwordx2 v[162:163], v[154:155], off offset:3072
	global_load_dwordx2 v[164:165], v[152:153], off offset:1024
	s_nop 0
	global_load_dwordx2 v[158:159], v[158:159], off offset:3072
	s_nop 0
	global_load_dwordx2 v[160:161], v[156:157], off offset:1024
	v_mad_i64_i32 v[152:153], vcc, v180, s2, v[2:3]
	v_lshl_add_u64 v[152:153], s[30:31], 0, v[152:153]
	v_add_co_u32_e32 v154, vcc, s76, v152
	s_nop 1
	v_addc_co_u32_e32 v155, vcc, 0, v153, vcc
	v_add_co_u32_e32 v152, vcc, s77, v152
	s_nop 1
	v_addc_co_u32_e32 v153, vcc, 0, v153, vcc
	v_mad_i64_i32 v[2:3], vcc, v181, s2, v[2:3]
	v_lshl_add_u64 v[2:3], s[30:31], 0, v[2:3]
	v_add_co_u32_e32 v190, vcc, s76, v2
	s_nop 1
	v_addc_co_u32_e32 v191, vcc, 0, v3, vcc
	v_add_co_u32_e32 v192, vcc, s77, v2
	s_waitcnt vmcnt(11)
	v_lshlrev_b32_e32 v2, 16, v182
	v_add_f32_e32 v2, v136, v2
	v_mul_f32_e32 v2, 0xbfb8aa3b, v2
	v_exp_f32_e32 v140, v2
	s_waitcnt vmcnt(8)
	v_lshlrev_b32_e32 v2, 16, v188
	v_add_f32_e32 v2, v132, v2
	v_mul_f32_e32 v2, 0xbfb8aa3b, v2
	v_exp_f32_e32 v141, v2
	v_addc_co_u32_e32 v193, vcc, 0, v3, vcc
	global_load_dwordx2 v[154:155], v[154:155], off offset:3072
	s_nop 0
	global_load_dwordx2 v[156:157], v[152:153], off offset:1024
	global_load_dwordx2 v[2:3], v[190:191], off offset:3072
	s_nop 0
	global_load_dwordx2 v[152:153], v[192:193], off offset:1024
	v_min_f32_e32 v190, 0x60ad78ec, v140
	v_min_f32_e32 v140, 0x60ad78ec, v141
	v_and_b32_e32 v141, 0xffff0000, v182
	v_add_f32_e32 v141, v137, v141
	v_mul_f32_e32 v141, 0xbfb8aa3b, v141
	v_exp_f32_e32 v141, v141
	v_and_b32_e32 v182, 0xffff0000, v188
	v_add_f32_e32 v182, v133, v182
	v_mul_f32_e32 v182, 0xbfb8aa3b, v182
	v_exp_f32_e32 v182, v182
	v_min_f32_e32 v191, 0x60ad78ec, v141
	v_lshlrev_b32_e32 v141, 16, v183
	v_add_f32_e32 v141, v138, v141
	v_mul_f32_e32 v141, 0xbfb8aa3b, v141
	v_add_f32_e32 v140, 1.0, v140
	v_exp_f32_e32 v141, v141
	v_rcp_f32_e32 v192, v140
	v_min_f32_e32 v140, 0x60ad78ec, v182
	v_lshlrev_b32_e32 v182, 16, v189
	v_add_f32_e32 v182, v134, v182
	v_mul_f32_e32 v182, 0xbfb8aa3b, v182
	v_exp_f32_e32 v188, v182
	v_min_f32_e32 v182, 0x60ad78ec, v141
	v_and_b32_e32 v141, 0xffff0000, v183
	v_and_b32_e32 v183, 0xffff0000, v189
	v_add_f32_e32 v183, v135, v183
	v_mul_f32_e32 v183, 0xbfb8aa3b, v183
	v_add_f32_e32 v141, v139, v141
	v_exp_f32_e32 v189, v183
	v_add_f32_e32 v140, 1.0, v140
	v_mul_f32_e32 v141, 0xbfb8aa3b, v141
	v_rcp_f32_e32 v193, v140
	v_min_f32_e32 v140, 0x60ad78ec, v188
	v_exp_f32_e32 v141, v141
	v_add_f32_e32 v140, 1.0, v140
	v_rcp_f32_e32 v188, v140
	v_min_f32_e32 v140, 0x60ad78ec, v189
	v_add_f32_e32 v140, 1.0, v140
	v_min_f32_e32 v183, 0x60ad78ec, v141
	v_rcp_f32_e32 v189, v140
	v_lshlrev_b32_e32 v140, 16, v186
	v_lshlrev_b32_e32 v141, 16, v184
	v_add_f32_e32 v140, v136, v140
	v_add_f32_e32 v141, v132, v141
	v_mul_f32_e32 v140, 0xbfb8aa3b, v140
	v_mul_f32_e32 v141, 0xbfb8aa3b, v141
	v_exp_f32_e32 v140, v140
	v_exp_f32_e32 v141, v141
	v_pk_add_f32 v[182:183], v[182:183], 1.0 op_sel_hi:[1,0]
	v_pk_add_f32 v[190:191], v[190:191], 1.0 op_sel_hi:[1,0]
	v_pk_mul_f32 v[182:183], v[182:183], v[188:189]
	v_pk_mul_f32 v[190:191], v[190:191], v[192:193]
	v_pk_mul_f32 v[126:127], v[126:127], v[182:183]
	v_min_f32_e32 v182, 0x60ad78ec, v140
	v_min_f32_e32 v140, 0x60ad78ec, v141
	v_and_b32_e32 v141, 0xffff0000, v186
	v_add_f32_e32 v141, v137, v141
	v_mul_f32_e32 v141, 0xbfb8aa3b, v141
	v_exp_f32_e32 v141, v141
	v_and_b32_e32 v183, 0xffff0000, v184
	v_add_f32_e32 v183, v133, v183
	v_mul_f32_e32 v183, 0xbfb8aa3b, v183
	v_exp_f32_e32 v184, v183
	v_min_f32_e32 v183, 0x60ad78ec, v141
	v_lshlrev_b32_e32 v141, 16, v187
	v_add_f32_e32 v141, v138, v141
	v_add_f32_e32 v140, 1.0, v140
	v_mul_f32_e32 v141, 0xbfb8aa3b, v141
	v_rcp_f32_e32 v188, v140
	v_min_f32_e32 v140, 0x60ad78ec, v184
	v_exp_f32_e32 v141, v141
	v_lshlrev_b32_e32 v184, 16, v185
	v_add_f32_e32 v184, v134, v184
	v_mul_f32_e32 v184, 0xbfb8aa3b, v184
	v_and_b32_e32 v185, 0xffff0000, v185
	v_exp_f32_e32 v186, v184
	v_add_f32_e32 v185, v135, v185
	v_min_f32_e32 v184, 0x60ad78ec, v141
	v_and_b32_e32 v141, 0xffff0000, v187
	v_mul_f32_e32 v185, 0xbfb8aa3b, v185
	v_add_f32_e32 v141, v139, v141
	v_exp_f32_e32 v187, v185
	v_add_f32_e32 v140, 1.0, v140
	v_mul_f32_e32 v141, 0xbfb8aa3b, v141
	v_rcp_f32_e32 v189, v140
	v_min_f32_e32 v140, 0x60ad78ec, v186
	v_exp_f32_e32 v141, v141
	v_add_f32_e32 v140, 1.0, v140
	v_rcp_f32_e32 v186, v140
	v_min_f32_e32 v140, 0x60ad78ec, v187
	v_add_f32_e32 v140, 1.0, v140
	v_min_f32_e32 v185, 0x60ad78ec, v141
	v_rcp_f32_e32 v187, v140
	s_waitcnt vmcnt(10)
	v_lshlrev_b32_e32 v140, 16, v172
	v_lshlrev_b32_e32 v141, 16, v170
	v_add_f32_e32 v140, v136, v140
	v_add_f32_e32 v141, v132, v141
	v_mul_f32_e32 v140, 0xbfb8aa3b, v140
	v_mul_f32_e32 v141, 0xbfb8aa3b, v141
	v_exp_f32_e32 v140, v140
	v_exp_f32_e32 v141, v141
	v_pk_add_f32 v[182:183], v[182:183], 1.0 op_sel_hi:[1,0]
	v_and_b32_e32 v170, 0xffff0000, v170
	v_pk_mul_f32 v[182:183], v[182:183], v[188:189]
	v_add_f32_e32 v170, v133, v170
	v_pk_mul_f32 v[108:109], v[108:109], v[182:183]
	v_min_f32_e32 v182, 0x60ad78ec, v140
	v_min_f32_e32 v140, 0x60ad78ec, v141
	v_and_b32_e32 v141, 0xffff0000, v172
	v_add_f32_e32 v141, v137, v141
	v_mul_f32_e32 v141, 0xbfb8aa3b, v141
	v_exp_f32_e32 v141, v141
	v_mul_f32_e32 v170, 0xbfb8aa3b, v170
	v_exp_f32_e32 v170, v170
	v_pk_add_f32 v[184:185], v[184:185], 1.0 op_sel_hi:[1,0]
	v_min_f32_e32 v183, 0x60ad78ec, v141
	v_lshlrev_b32_e32 v141, 16, v173
	v_add_f32_e32 v141, v138, v141
	v_pk_mul_f32 v[184:185], v[184:185], v[186:187]
	v_add_f32_e32 v140, 1.0, v140
	v_mul_f32_e32 v141, 0xbfb8aa3b, v141
	v_pk_mul_f32 v[110:111], v[110:111], v[184:185]
	v_rcp_f32_e32 v184, v140
	v_min_f32_e32 v140, 0x60ad78ec, v170
	v_exp_f32_e32 v141, v141
	v_lshlrev_b32_e32 v170, 16, v171
	v_add_f32_e32 v170, v134, v170
	v_mul_f32_e32 v170, 0xbfb8aa3b, v170
	v_and_b32_e32 v171, 0xffff0000, v171
	v_exp_f32_e32 v172, v170
	v_add_f32_e32 v171, v135, v171
	v_min_f32_e32 v170, 0x60ad78ec, v141
	v_and_b32_e32 v141, 0xffff0000, v173
	v_mul_f32_e32 v171, 0xbfb8aa3b, v171
	v_add_f32_e32 v141, v139, v141
	v_exp_f32_e32 v173, v171
	v_add_f32_e32 v140, 1.0, v140
	v_mul_f32_e32 v141, 0xbfb8aa3b, v141
	v_rcp_f32_e32 v185, v140
	v_min_f32_e32 v140, 0x60ad78ec, v172
	v_exp_f32_e32 v141, v141
	v_add_f32_e32 v140, 1.0, v140
	v_rcp_f32_e32 v172, v140
	v_min_f32_e32 v140, 0x60ad78ec, v173
	v_add_f32_e32 v140, 1.0, v140
	v_min_f32_e32 v171, 0x60ad78ec, v141
	v_rcp_f32_e32 v173, v140
	s_waitcnt vmcnt(8)
	v_lshlrev_b32_e32 v140, 16, v168
	v_lshlrev_b32_e32 v141, 16, v166
	v_add_f32_e32 v140, v136, v140
	v_add_f32_e32 v141, v132, v141
	v_mul_f32_e32 v140, 0xbfb8aa3b, v140
	v_mul_f32_e32 v141, 0xbfb8aa3b, v141
	v_exp_f32_e32 v140, v140
	v_exp_f32_e32 v141, v141
	v_pk_add_f32 v[170:171], v[170:171], 1.0 op_sel_hi:[1,0]
	v_and_b32_e32 v166, 0xffff0000, v166
	v_pk_mul_f32 v[170:171], v[170:171], v[172:173]
	v_add_f32_e32 v166, v133, v166
	v_pk_mul_f32 v[94:95], v[94:95], v[170:171]
	v_min_f32_e32 v170, 0x60ad78ec, v140
	v_min_f32_e32 v140, 0x60ad78ec, v141
	v_and_b32_e32 v141, 0xffff0000, v168
	v_add_f32_e32 v141, v137, v141
	v_mul_f32_e32 v141, 0xbfb8aa3b, v141
	v_exp_f32_e32 v141, v141
	v_mul_f32_e32 v166, 0xbfb8aa3b, v166
	v_exp_f32_e32 v166, v166
	v_add_f32_e32 v140, 1.0, v140
	v_min_f32_e32 v171, 0x60ad78ec, v141
	v_lshlrev_b32_e32 v141, 16, v169
	v_add_f32_e32 v141, v138, v141
	v_mul_f32_e32 v141, 0xbfb8aa3b, v141
	v_rcp_f32_e32 v172, v140
	v_min_f32_e32 v140, 0x60ad78ec, v166
	v_exp_f32_e32 v141, v141
	v_lshlrev_b32_e32 v166, 16, v167
	v_add_f32_e32 v166, v134, v166
	v_mul_f32_e32 v166, 0xbfb8aa3b, v166
	v_and_b32_e32 v167, 0xffff0000, v167
	v_exp_f32_e32 v168, v166
	v_add_f32_e32 v167, v135, v167
	v_min_f32_e32 v166, 0x60ad78ec, v141
	v_and_b32_e32 v141, 0xffff0000, v169
	v_mul_f32_e32 v167, 0xbfb8aa3b, v167
	v_add_f32_e32 v141, v139, v141
	v_exp_f32_e32 v169, v167
	v_add_f32_e32 v140, 1.0, v140
	v_mul_f32_e32 v141, 0xbfb8aa3b, v141
	v_rcp_f32_e32 v173, v140
	v_min_f32_e32 v140, 0x60ad78ec, v168
	v_exp_f32_e32 v141, v141
	v_add_f32_e32 v140, 1.0, v140
	v_rcp_f32_e32 v168, v140
	v_min_f32_e32 v140, 0x60ad78ec, v169
	v_add_f32_e32 v140, 1.0, v140
	v_min_f32_e32 v167, 0x60ad78ec, v141
	v_rcp_f32_e32 v169, v140
	s_waitcnt vmcnt(6)
	v_lshlrev_b32_e32 v140, 16, v164
	v_lshlrev_b32_e32 v141, 16, v162
	v_add_f32_e32 v140, v136, v140
	v_add_f32_e32 v141, v132, v141
	v_mul_f32_e32 v140, 0xbfb8aa3b, v140
	v_mul_f32_e32 v141, 0xbfb8aa3b, v141
	v_exp_f32_e32 v140, v140
	v_exp_f32_e32 v141, v141
	v_pk_add_f32 v[166:167], v[166:167], 1.0 op_sel_hi:[1,0]
	v_and_b32_e32 v162, 0xffff0000, v162
	v_pk_mul_f32 v[166:167], v[166:167], v[168:169]
	v_add_f32_e32 v162, v133, v162
	v_pk_mul_f32 v[78:79], v[78:79], v[166:167]
	v_min_f32_e32 v166, 0x60ad78ec, v140
	v_min_f32_e32 v140, 0x60ad78ec, v141
	v_and_b32_e32 v141, 0xffff0000, v164
	v_add_f32_e32 v141, v137, v141
	v_mul_f32_e32 v141, 0xbfb8aa3b, v141
	v_exp_f32_e32 v141, v141
	v_mul_f32_e32 v162, 0xbfb8aa3b, v162
	v_exp_f32_e32 v162, v162
	v_add_f32_e32 v140, 1.0, v140
	v_min_f32_e32 v167, 0x60ad78ec, v141
	v_lshlrev_b32_e32 v141, 16, v165
	v_add_f32_e32 v141, v138, v141
	v_mul_f32_e32 v141, 0xbfb8aa3b, v141
	v_rcp_f32_e32 v168, v140
	v_min_f32_e32 v140, 0x60ad78ec, v162
	v_exp_f32_e32 v141, v141
	v_lshlrev_b32_e32 v162, 16, v163
	v_add_f32_e32 v162, v134, v162
	v_mul_f32_e32 v162, 0xbfb8aa3b, v162
	v_and_b32_e32 v163, 0xffff0000, v163
	v_exp_f32_e32 v164, v162
	v_add_f32_e32 v163, v135, v163
	v_min_f32_e32 v162, 0x60ad78ec, v141
	v_and_b32_e32 v141, 0xffff0000, v165
	v_mul_f32_e32 v163, 0xbfb8aa3b, v163
	v_add_f32_e32 v141, v139, v141
	v_exp_f32_e32 v165, v163
	v_add_f32_e32 v140, 1.0, v140
	v_mul_f32_e32 v141, 0xbfb8aa3b, v141
	v_rcp_f32_e32 v169, v140
	v_min_f32_e32 v140, 0x60ad78ec, v164
	v_exp_f32_e32 v141, v141
	v_add_f32_e32 v140, 1.0, v140
	v_rcp_f32_e32 v164, v140
	v_min_f32_e32 v140, 0x60ad78ec, v165
	v_add_f32_e32 v140, 1.0, v140
	v_min_f32_e32 v163, 0x60ad78ec, v141
	v_rcp_f32_e32 v165, v140
	s_waitcnt vmcnt(4)
	v_lshlrev_b32_e32 v140, 16, v160
	v_lshlrev_b32_e32 v141, 16, v158
	v_add_f32_e32 v140, v136, v140
	v_add_f32_e32 v141, v132, v141
	v_mul_f32_e32 v140, 0xbfb8aa3b, v140
	v_mul_f32_e32 v141, 0xbfb8aa3b, v141
	v_exp_f32_e32 v140, v140
	v_exp_f32_e32 v141, v141
	v_pk_add_f32 v[162:163], v[162:163], 1.0 op_sel_hi:[1,0]
	v_and_b32_e32 v158, 0xffff0000, v158
	v_pk_mul_f32 v[162:163], v[162:163], v[164:165]
	v_add_f32_e32 v158, v133, v158
	v_pk_mul_f32 v[62:63], v[62:63], v[162:163]
	v_min_f32_e32 v162, 0x60ad78ec, v140
	v_min_f32_e32 v140, 0x60ad78ec, v141
	v_and_b32_e32 v141, 0xffff0000, v160
	v_add_f32_e32 v141, v137, v141
	v_mul_f32_e32 v141, 0xbfb8aa3b, v141
	v_exp_f32_e32 v141, v141
	v_mul_f32_e32 v158, 0xbfb8aa3b, v158
	v_exp_f32_e32 v158, v158
	v_add_f32_e32 v140, 1.0, v140
	v_min_f32_e32 v163, 0x60ad78ec, v141
	v_lshlrev_b32_e32 v141, 16, v161
	v_add_f32_e32 v141, v138, v141
	v_mul_f32_e32 v141, 0xbfb8aa3b, v141
	v_rcp_f32_e32 v164, v140
	v_min_f32_e32 v140, 0x60ad78ec, v158
	v_exp_f32_e32 v141, v141
	v_lshlrev_b32_e32 v158, 16, v159
	v_add_f32_e32 v158, v134, v158
	v_mul_f32_e32 v158, 0xbfb8aa3b, v158
	v_and_b32_e32 v159, 0xffff0000, v159
	v_exp_f32_e32 v160, v158
	v_add_f32_e32 v159, v135, v159
	v_min_f32_e32 v158, 0x60ad78ec, v141
	v_and_b32_e32 v141, 0xffff0000, v161
	v_mul_f32_e32 v159, 0xbfb8aa3b, v159
	v_add_f32_e32 v141, v139, v141
	v_exp_f32_e32 v161, v159
	v_add_f32_e32 v140, 1.0, v140
	v_mul_f32_e32 v141, 0xbfb8aa3b, v141
	v_rcp_f32_e32 v165, v140
	v_min_f32_e32 v140, 0x60ad78ec, v160
	v_exp_f32_e32 v141, v141
	v_add_f32_e32 v140, 1.0, v140
	v_rcp_f32_e32 v160, v140
	v_min_f32_e32 v140, 0x60ad78ec, v161
	v_add_f32_e32 v140, 1.0, v140
	v_min_f32_e32 v159, 0x60ad78ec, v141
	v_rcp_f32_e32 v161, v140
	s_waitcnt vmcnt(2)
	v_lshlrev_b32_e32 v140, 16, v156
	v_lshlrev_b32_e32 v141, 16, v154
	v_add_f32_e32 v140, v136, v140
	v_add_f32_e32 v141, v132, v141
	v_mul_f32_e32 v140, 0xbfb8aa3b, v140
	v_mul_f32_e32 v141, 0xbfb8aa3b, v141
	v_exp_f32_e32 v140, v140
	v_exp_f32_e32 v141, v141
	v_pk_add_f32 v[158:159], v[158:159], 1.0 op_sel_hi:[1,0]
	v_and_b32_e32 v154, 0xffff0000, v154
	v_pk_mul_f32 v[158:159], v[158:159], v[160:161]
	v_add_f32_e32 v154, v133, v154
	v_pk_mul_f32 v[46:47], v[46:47], v[158:159]
	v_min_f32_e32 v158, 0x60ad78ec, v140
	v_min_f32_e32 v140, 0x60ad78ec, v141
	v_and_b32_e32 v141, 0xffff0000, v156
	v_add_f32_e32 v141, v137, v141
	v_mul_f32_e32 v141, 0xbfb8aa3b, v141
	v_exp_f32_e32 v141, v141
	v_mul_f32_e32 v154, 0xbfb8aa3b, v154
	v_exp_f32_e32 v154, v154
	v_add_f32_e32 v140, 1.0, v140
	v_min_f32_e32 v159, 0x60ad78ec, v141
	v_lshlrev_b32_e32 v141, 16, v157
	v_add_f32_e32 v141, v138, v141
	v_rcp_f32_e32 v160, v140
	v_min_f32_e32 v140, 0x60ad78ec, v154
	v_mul_f32_e32 v141, 0xbfb8aa3b, v141
	v_lshlrev_b32_e32 v154, 16, v155
	v_exp_f32_e32 v141, v141
	v_add_f32_e32 v154, v134, v154
	v_mul_f32_e32 v154, 0xbfb8aa3b, v154
	v_and_b32_e32 v155, 0xffff0000, v155
	v_exp_f32_e32 v156, v154
	v_add_f32_e32 v155, v135, v155
	v_mul_f32_e32 v155, 0xbfb8aa3b, v155
	v_min_f32_e32 v154, 0x60ad78ec, v141
	v_and_b32_e32 v141, 0xffff0000, v157
	v_exp_f32_e32 v157, v155
	v_add_f32_e32 v140, 1.0, v140
	v_rcp_f32_e32 v161, v140
	v_min_f32_e32 v140, 0x60ad78ec, v156
	v_add_f32_e32 v140, 1.0, v140
	v_rcp_f32_e32 v156, v140
	v_min_f32_e32 v140, 0x60ad78ec, v157
	v_add_f32_e32 v140, 1.0, v140
	v_rcp_f32_e32 v157, v140
	s_waitcnt vmcnt(0)
	v_lshlrev_b32_e32 v140, 16, v152
	v_add_f32_e32 v136, v136, v140
	v_lshlrev_b32_e32 v140, 16, v2
	v_add_f32_e32 v132, v132, v140
	v_mul_f32_e32 v136, 0xbfb8aa3b, v136
	v_mul_f32_e32 v132, 0xbfb8aa3b, v132
	v_exp_f32_e32 v136, v136
	v_exp_f32_e32 v140, v132
	v_and_b32_e32 v2, 0xffff0000, v2
	v_add_f32_e32 v2, v133, v2
	v_min_f32_e32 v132, 0x60ad78ec, v136
	v_min_f32_e32 v136, 0x60ad78ec, v140
	v_and_b32_e32 v140, 0xffff0000, v152
	v_add_f32_e32 v137, v137, v140
	v_mul_f32_e32 v137, 0xbfb8aa3b, v137
	v_exp_f32_e32 v137, v137
	v_add_f32_e32 v133, 1.0, v136
	v_mul_f32_e32 v2, 0xbfb8aa3b, v2
	v_rcp_f32_e32 v136, v133
	v_min_f32_e32 v133, 0x60ad78ec, v137
	v_lshlrev_b32_e32 v137, 16, v153
	v_exp_f32_e32 v2, v2
	v_add_f32_e32 v137, v138, v137
	v_mul_f32_e32 v137, 0xbfb8aa3b, v137
	v_exp_f32_e32 v138, v137
	v_lshlrev_b32_e32 v137, 16, v3
	v_and_b32_e32 v3, 0xffff0000, v3
	v_add_f32_e32 v134, v134, v137
	v_add_f32_e32 v3, v135, v3
	v_min_f32_e32 v2, 0x60ad78ec, v2
	v_mul_f32_e32 v134, 0xbfb8aa3b, v134
	v_mul_f32_e32 v3, 0xbfb8aa3b, v3
	v_exp_f32_e32 v134, v134
	v_add_f32_e32 v2, 1.0, v2
	v_exp_f32_e32 v135, v3
	v_rcp_f32_e32 v137, v2
	v_min_f32_e32 v2, 0x60ad78ec, v138
	v_and_b32_e32 v138, 0xffff0000, v153
	v_add_f32_e32 v138, v139, v138
	v_mul_f32_e32 v138, 0xbfb8aa3b, v138
	v_min_f32_e32 v134, 0x60ad78ec, v134
	v_exp_f32_e32 v138, v138
	v_min_f32_e32 v135, 0x60ad78ec, v135
	v_add_f32_e32 v141, v139, v141
	v_add_f32_e32 v3, 1.0, v134
	v_add_f32_e32 v135, 1.0, v135
	v_mul_f32_e32 v141, 0xbfb8aa3b, v141
	v_rcp_f32_e32 v134, v3
	v_rcp_f32_e32 v135, v135
	v_exp_f32_e32 v141, v141
	v_min_f32_e32 v3, 0x60ad78ec, v138
	v_pk_add_f32 v[2:3], v[2:3], 1.0 op_sel_hi:[1,0]
	v_pk_add_f32 v[132:133], v[132:133], 1.0 op_sel_hi:[1,0]
	v_pk_mul_f32 v[2:3], v[2:3], v[134:135]
	v_min_f32_e32 v155, 0x60ad78ec, v141
	v_pk_mul_f32 v[14:15], v[14:15], v[2:3]
	v_add_u32_e32 v2, s82, v0
	v_pk_add_f32 v[154:155], v[154:155], 1.0 op_sel_hi:[1,0]
	v_ashrrev_i32_e32 v3, 31, v2
	v_pk_mul_f32 v[154:155], v[154:155], v[156:157]
	v_pk_mul_f32 v[152:153], v[132:133], v[136:137]
	v_lshl_add_u64 v[136:137], v[2:3], 2, s[6:7]
	v_lshlrev_b64 v[2:3], 1, v[2:3]
	v_pk_mul_f32 v[30:31], v[30:31], v[154:155]
	v_mad_i64_i32 v[154:155], vcc, v174, s2, v[2:3]
	v_lshl_add_u64 v[154:155], s[30:31], 0, v[154:155]
	v_add_co_u32_e32 v156, vcc, s76, v154
	v_pk_add_f32 v[182:183], v[182:183], 1.0 op_sel_hi:[1,0]
	s_nop 0
	v_addc_co_u32_e32 v157, vcc, 0, v155, vcc
	v_add_co_u32_e32 v154, vcc, s77, v154
	v_pk_mul_f32 v[182:183], v[182:183], v[184:185]
	s_nop 0
	v_addc_co_u32_e32 v155, vcc, 0, v155, vcc
	v_pk_mul_f32 v[92:93], v[92:93], v[182:183]
	v_pk_add_f32 v[158:159], v[158:159], 1.0 op_sel_hi:[1,0]
	global_load_dwordx4 v[132:135], v[136:137], off offset:-4096
	s_nop 0
	global_load_dwordx4 v[136:139], v[136:137], off
	v_pk_mul_f32 v[158:159], v[158:159], v[160:161]
	global_load_dwordx2 v[182:183], v[154:155], off offset:1024
	v_mad_i64_i32 v[154:155], vcc, v175, s2, v[2:3]
	v_lshl_add_u64 v[154:155], s[30:31], 0, v[154:155]
	v_pk_mul_f32 v[28:29], v[28:29], v[158:159]
	v_add_co_u32_e32 v158, vcc, s76, v154
	v_pk_mul_f32 v[12:13], v[12:13], v[152:153]
	s_nop 0
	v_addc_co_u32_e32 v159, vcc, 0, v155, vcc
	v_add_co_u32_e32 v154, vcc, s77, v154
	v_pk_add_f32 v[170:171], v[170:171], 1.0 op_sel_hi:[1,0]
	s_nop 0
	v_addc_co_u32_e32 v155, vcc, 0, v155, vcc
	global_load_dwordx2 v[184:185], v[158:159], off offset:3072
	global_load_dwordx2 v[186:187], v[154:155], off offset:1024
	global_load_dwordx2 v[188:189], v[156:157], off offset:3072
	v_mad_i64_i32 v[152:153], vcc, v176, s2, v[2:3]
	v_lshl_add_u64 v[152:153], s[30:31], 0, v[152:153]
	v_add_co_u32_e32 v154, vcc, s76, v152
	v_pk_add_f32 v[166:167], v[166:167], 1.0 op_sel_hi:[1,0]
	s_nop 0
	v_addc_co_u32_e32 v155, vcc, 0, v153, vcc
	v_add_co_u32_e32 v152, vcc, s77, v152
	v_pk_mul_f32 v[170:171], v[170:171], v[172:173]
	s_nop 0
	v_addc_co_u32_e32 v153, vcc, 0, v153, vcc
	v_mad_i64_i32 v[156:157], vcc, v177, s2, v[2:3]
	v_lshl_add_u64 v[156:157], s[30:31], 0, v[156:157]
	v_add_co_u32_e32 v158, vcc, s76, v156
	v_pk_mul_f32 v[166:167], v[166:167], v[168:169]
	s_nop 0
	v_addc_co_u32_e32 v159, vcc, 0, v157, vcc
	v_add_co_u32_e32 v156, vcc, s77, v156
	v_pk_mul_f32 v[76:77], v[76:77], v[170:171]
	v_pk_mul_f32 v[60:61], v[60:61], v[166:167]
	v_addc_co_u32_e32 v157, vcc, 0, v157, vcc
	global_load_dwordx2 v[170:171], v[154:155], off offset:3072
	global_load_dwordx2 v[172:173], v[152:153], off offset:1024
	global_load_dwordx2 v[166:167], v[158:159], off offset:3072
	global_load_dwordx2 v[168:169], v[156:157], off offset:1024
	v_mad_i64_i32 v[152:153], vcc, v178, s2, v[2:3]
	v_lshl_add_u64 v[152:153], s[30:31], 0, v[152:153]
	v_add_co_u32_e32 v154, vcc, s76, v152
	v_pk_add_f32 v[162:163], v[162:163], 1.0 op_sel_hi:[1,0]
	s_nop 0
	v_addc_co_u32_e32 v155, vcc, 0, v153, vcc
	v_add_co_u32_e32 v152, vcc, s77, v152
	v_pk_mul_f32 v[162:163], v[162:163], v[164:165]
	s_nop 0
	v_addc_co_u32_e32 v153, vcc, 0, v153, vcc
	v_mad_i64_i32 v[156:157], vcc, v179, s2, v[2:3]
	v_lshl_add_u64 v[156:157], s[30:31], 0, v[156:157]
	v_add_co_u32_e32 v158, vcc, s76, v156
	v_pk_mul_f32 v[44:45], v[44:45], v[162:163]
	s_nop 0
	v_addc_co_u32_e32 v159, vcc, 0, v157, vcc
	v_add_co_u32_e32 v156, vcc, s77, v156
	v_pk_mul_f32 v[124:125], v[124:125], v[190:191]
	s_nop 0
	v_addc_co_u32_e32 v157, vcc, 0, v157, vcc
	global_load_dwordx2 v[162:163], v[154:155], off offset:3072
	global_load_dwordx2 v[164:165], v[152:153], off offset:1024
	s_nop 0
	global_load_dwordx2 v[158:159], v[158:159], off offset:3072
	s_nop 0
	global_load_dwordx2 v[160:161], v[156:157], off offset:1024
	v_mad_i64_i32 v[152:153], vcc, v180, s2, v[2:3]
	v_lshl_add_u64 v[152:153], s[30:31], 0, v[152:153]
	v_add_co_u32_e32 v154, vcc, s76, v152
	s_nop 1
	v_addc_co_u32_e32 v155, vcc, 0, v153, vcc
	v_add_co_u32_e32 v152, vcc, s77, v152
	s_nop 1
	v_addc_co_u32_e32 v153, vcc, 0, v153, vcc
	v_mad_i64_i32 v[2:3], vcc, v181, s2, v[2:3]
	v_lshl_add_u64 v[2:3], s[30:31], 0, v[2:3]
	v_add_co_u32_e32 v190, vcc, s76, v2
	s_nop 1
	v_addc_co_u32_e32 v191, vcc, 0, v3, vcc
	v_add_co_u32_e32 v192, vcc, s77, v2
	s_waitcnt vmcnt(11)
	v_lshlrev_b32_e32 v2, 16, v182
	v_add_f32_e32 v2, v136, v2
	v_mul_f32_e32 v2, 0xbfb8aa3b, v2
	v_exp_f32_e32 v140, v2
	s_waitcnt vmcnt(8)
	v_lshlrev_b32_e32 v2, 16, v188
	v_add_f32_e32 v2, v132, v2
	v_mul_f32_e32 v2, 0xbfb8aa3b, v2
	v_exp_f32_e32 v141, v2
	v_addc_co_u32_e32 v193, vcc, 0, v3, vcc
	global_load_dwordx2 v[154:155], v[154:155], off offset:3072
	s_nop 0
	global_load_dwordx2 v[156:157], v[152:153], off offset:1024
	global_load_dwordx2 v[2:3], v[190:191], off offset:3072
	s_nop 0
	global_load_dwordx2 v[152:153], v[192:193], off offset:1024
	v_min_f32_e32 v190, 0x60ad78ec, v140
	v_min_f32_e32 v140, 0x60ad78ec, v141
	v_and_b32_e32 v141, 0xffff0000, v182
	v_add_f32_e32 v141, v137, v141
	v_mul_f32_e32 v141, 0xbfb8aa3b, v141
	v_exp_f32_e32 v141, v141
	v_and_b32_e32 v182, 0xffff0000, v188
	v_add_f32_e32 v182, v133, v182
	v_mul_f32_e32 v182, 0xbfb8aa3b, v182
	v_exp_f32_e32 v182, v182
	v_min_f32_e32 v191, 0x60ad78ec, v141
	v_lshlrev_b32_e32 v141, 16, v183
	v_add_f32_e32 v141, v138, v141
	v_mul_f32_e32 v141, 0xbfb8aa3b, v141
	v_add_f32_e32 v140, 1.0, v140
	v_exp_f32_e32 v141, v141
	v_rcp_f32_e32 v192, v140
	v_min_f32_e32 v140, 0x60ad78ec, v182
	v_lshlrev_b32_e32 v182, 16, v189
	v_add_f32_e32 v182, v134, v182
	v_mul_f32_e32 v182, 0xbfb8aa3b, v182
	v_exp_f32_e32 v188, v182
	v_min_f32_e32 v182, 0x60ad78ec, v141
	v_and_b32_e32 v141, 0xffff0000, v183
	v_and_b32_e32 v183, 0xffff0000, v189
	v_add_f32_e32 v183, v135, v183
	v_mul_f32_e32 v183, 0xbfb8aa3b, v183
	v_add_f32_e32 v141, v139, v141
	v_exp_f32_e32 v189, v183
	v_add_f32_e32 v140, 1.0, v140
	v_mul_f32_e32 v141, 0xbfb8aa3b, v141
	v_rcp_f32_e32 v193, v140
	v_min_f32_e32 v140, 0x60ad78ec, v188
	v_exp_f32_e32 v141, v141
	v_add_f32_e32 v140, 1.0, v140
	v_rcp_f32_e32 v188, v140
	v_min_f32_e32 v140, 0x60ad78ec, v189
	v_add_f32_e32 v140, 1.0, v140
	v_min_f32_e32 v183, 0x60ad78ec, v141
	v_rcp_f32_e32 v189, v140
	v_lshlrev_b32_e32 v140, 16, v186
	v_lshlrev_b32_e32 v141, 16, v184
	v_add_f32_e32 v140, v136, v140
	v_add_f32_e32 v141, v132, v141
	v_mul_f32_e32 v140, 0xbfb8aa3b, v140
	v_mul_f32_e32 v141, 0xbfb8aa3b, v141
	v_exp_f32_e32 v140, v140
	v_exp_f32_e32 v141, v141
	v_pk_add_f32 v[182:183], v[182:183], 1.0 op_sel_hi:[1,0]
	v_pk_add_f32 v[190:191], v[190:191], 1.0 op_sel_hi:[1,0]
	v_pk_mul_f32 v[182:183], v[182:183], v[188:189]
	v_pk_mul_f32 v[190:191], v[190:191], v[192:193]
	v_pk_mul_f32 v[122:123], v[122:123], v[182:183]
	v_min_f32_e32 v182, 0x60ad78ec, v140
	v_min_f32_e32 v140, 0x60ad78ec, v141
	v_and_b32_e32 v141, 0xffff0000, v186
	v_add_f32_e32 v141, v137, v141
	v_mul_f32_e32 v141, 0xbfb8aa3b, v141
	v_exp_f32_e32 v141, v141
	v_and_b32_e32 v183, 0xffff0000, v184
	v_add_f32_e32 v183, v133, v183
	v_mul_f32_e32 v183, 0xbfb8aa3b, v183
	v_exp_f32_e32 v184, v183
	v_min_f32_e32 v183, 0x60ad78ec, v141
	v_lshlrev_b32_e32 v141, 16, v187
	v_add_f32_e32 v141, v138, v141
	v_add_f32_e32 v140, 1.0, v140
	v_mul_f32_e32 v141, 0xbfb8aa3b, v141
	v_rcp_f32_e32 v188, v140
	v_min_f32_e32 v140, 0x60ad78ec, v184
	v_exp_f32_e32 v141, v141
	v_lshlrev_b32_e32 v184, 16, v185
	v_add_f32_e32 v184, v134, v184
	v_mul_f32_e32 v184, 0xbfb8aa3b, v184
	v_and_b32_e32 v185, 0xffff0000, v185
	v_exp_f32_e32 v186, v184
	v_add_f32_e32 v185, v135, v185
	v_min_f32_e32 v184, 0x60ad78ec, v141
	v_and_b32_e32 v141, 0xffff0000, v187
	v_mul_f32_e32 v185, 0xbfb8aa3b, v185
	v_add_f32_e32 v141, v139, v141
	v_exp_f32_e32 v187, v185
	v_add_f32_e32 v140, 1.0, v140
	v_mul_f32_e32 v141, 0xbfb8aa3b, v141
	v_rcp_f32_e32 v189, v140
	v_min_f32_e32 v140, 0x60ad78ec, v186
	v_exp_f32_e32 v141, v141
	v_add_f32_e32 v140, 1.0, v140
	v_rcp_f32_e32 v186, v140
	v_min_f32_e32 v140, 0x60ad78ec, v187
	v_add_f32_e32 v140, 1.0, v140
	v_min_f32_e32 v185, 0x60ad78ec, v141
	v_rcp_f32_e32 v187, v140
	s_waitcnt vmcnt(10)
	v_lshlrev_b32_e32 v140, 16, v172
	v_lshlrev_b32_e32 v141, 16, v170
	v_add_f32_e32 v140, v136, v140
	v_add_f32_e32 v141, v132, v141
	v_mul_f32_e32 v140, 0xbfb8aa3b, v140
	v_mul_f32_e32 v141, 0xbfb8aa3b, v141
	v_exp_f32_e32 v140, v140
	v_exp_f32_e32 v141, v141
	v_pk_add_f32 v[182:183], v[182:183], 1.0 op_sel_hi:[1,0]
	v_and_b32_e32 v170, 0xffff0000, v170
	v_pk_mul_f32 v[182:183], v[182:183], v[188:189]
	v_add_f32_e32 v170, v133, v170
	v_pk_mul_f32 v[104:105], v[104:105], v[182:183]
	v_min_f32_e32 v182, 0x60ad78ec, v140
	v_min_f32_e32 v140, 0x60ad78ec, v141
	v_and_b32_e32 v141, 0xffff0000, v172
	v_add_f32_e32 v141, v137, v141
	v_mul_f32_e32 v141, 0xbfb8aa3b, v141
	v_exp_f32_e32 v141, v141
	v_mul_f32_e32 v170, 0xbfb8aa3b, v170
	v_exp_f32_e32 v170, v170
	v_pk_add_f32 v[184:185], v[184:185], 1.0 op_sel_hi:[1,0]
	v_min_f32_e32 v183, 0x60ad78ec, v141
	v_lshlrev_b32_e32 v141, 16, v173
	v_add_f32_e32 v141, v138, v141
	v_pk_mul_f32 v[184:185], v[184:185], v[186:187]
	v_add_f32_e32 v140, 1.0, v140
	v_mul_f32_e32 v141, 0xbfb8aa3b, v141
	v_pk_mul_f32 v[106:107], v[106:107], v[184:185]
	v_rcp_f32_e32 v184, v140
	v_min_f32_e32 v140, 0x60ad78ec, v170
	v_exp_f32_e32 v141, v141
	v_lshlrev_b32_e32 v170, 16, v171
	v_add_f32_e32 v170, v134, v170
	v_mul_f32_e32 v170, 0xbfb8aa3b, v170
	v_and_b32_e32 v171, 0xffff0000, v171
	v_exp_f32_e32 v172, v170
	v_add_f32_e32 v171, v135, v171
	v_min_f32_e32 v170, 0x60ad78ec, v141
	v_and_b32_e32 v141, 0xffff0000, v173
	v_mul_f32_e32 v171, 0xbfb8aa3b, v171
	v_add_f32_e32 v141, v139, v141
	v_exp_f32_e32 v173, v171
	v_add_f32_e32 v140, 1.0, v140
	v_mul_f32_e32 v141, 0xbfb8aa3b, v141
	v_rcp_f32_e32 v185, v140
	v_min_f32_e32 v140, 0x60ad78ec, v172
	v_exp_f32_e32 v141, v141
	v_add_f32_e32 v140, 1.0, v140
	v_rcp_f32_e32 v172, v140
	v_min_f32_e32 v140, 0x60ad78ec, v173
	v_add_f32_e32 v140, 1.0, v140
	v_min_f32_e32 v171, 0x60ad78ec, v141
	v_rcp_f32_e32 v173, v140
	s_waitcnt vmcnt(8)
	v_lshlrev_b32_e32 v140, 16, v168
	v_lshlrev_b32_e32 v141, 16, v166
	v_add_f32_e32 v140, v136, v140
	v_add_f32_e32 v141, v132, v141
	v_mul_f32_e32 v140, 0xbfb8aa3b, v140
	v_mul_f32_e32 v141, 0xbfb8aa3b, v141
	v_exp_f32_e32 v140, v140
	v_exp_f32_e32 v141, v141
	v_pk_add_f32 v[170:171], v[170:171], 1.0 op_sel_hi:[1,0]
	v_and_b32_e32 v166, 0xffff0000, v166
	v_pk_mul_f32 v[170:171], v[170:171], v[172:173]
	v_add_f32_e32 v166, v133, v166
	v_pk_mul_f32 v[90:91], v[90:91], v[170:171]
	v_min_f32_e32 v170, 0x60ad78ec, v140
	v_min_f32_e32 v140, 0x60ad78ec, v141
	v_and_b32_e32 v141, 0xffff0000, v168
	v_add_f32_e32 v141, v137, v141
	v_mul_f32_e32 v141, 0xbfb8aa3b, v141
	v_exp_f32_e32 v141, v141
	v_mul_f32_e32 v166, 0xbfb8aa3b, v166
	v_exp_f32_e32 v166, v166
	v_add_f32_e32 v140, 1.0, v140
	v_min_f32_e32 v171, 0x60ad78ec, v141
	v_lshlrev_b32_e32 v141, 16, v169
	v_add_f32_e32 v141, v138, v141
	v_mul_f32_e32 v141, 0xbfb8aa3b, v141
	v_rcp_f32_e32 v172, v140
	v_min_f32_e32 v140, 0x60ad78ec, v166
	v_exp_f32_e32 v141, v141
	v_lshlrev_b32_e32 v166, 16, v167
	v_add_f32_e32 v166, v134, v166
	v_mul_f32_e32 v166, 0xbfb8aa3b, v166
	v_and_b32_e32 v167, 0xffff0000, v167
	v_exp_f32_e32 v168, v166
	v_add_f32_e32 v167, v135, v167
	v_min_f32_e32 v166, 0x60ad78ec, v141
	v_and_b32_e32 v141, 0xffff0000, v169
	v_mul_f32_e32 v167, 0xbfb8aa3b, v167
	v_add_f32_e32 v141, v139, v141
	v_exp_f32_e32 v169, v167
	v_add_f32_e32 v140, 1.0, v140
	v_mul_f32_e32 v141, 0xbfb8aa3b, v141
	v_rcp_f32_e32 v173, v140
	v_min_f32_e32 v140, 0x60ad78ec, v168
	v_exp_f32_e32 v141, v141
	v_add_f32_e32 v140, 1.0, v140
	v_rcp_f32_e32 v168, v140
	v_min_f32_e32 v140, 0x60ad78ec, v169
	v_add_f32_e32 v140, 1.0, v140
	v_min_f32_e32 v167, 0x60ad78ec, v141
	v_rcp_f32_e32 v169, v140
	s_waitcnt vmcnt(6)
	v_lshlrev_b32_e32 v140, 16, v164
	v_lshlrev_b32_e32 v141, 16, v162
	v_add_f32_e32 v140, v136, v140
	v_add_f32_e32 v141, v132, v141
	v_mul_f32_e32 v140, 0xbfb8aa3b, v140
	v_mul_f32_e32 v141, 0xbfb8aa3b, v141
	v_exp_f32_e32 v140, v140
	v_exp_f32_e32 v141, v141
	v_pk_add_f32 v[166:167], v[166:167], 1.0 op_sel_hi:[1,0]
	v_and_b32_e32 v162, 0xffff0000, v162
	v_pk_mul_f32 v[166:167], v[166:167], v[168:169]
	v_add_f32_e32 v162, v133, v162
	v_pk_mul_f32 v[74:75], v[74:75], v[166:167]
	v_min_f32_e32 v166, 0x60ad78ec, v140
	v_min_f32_e32 v140, 0x60ad78ec, v141
	v_and_b32_e32 v141, 0xffff0000, v164
	v_add_f32_e32 v141, v137, v141
	v_mul_f32_e32 v141, 0xbfb8aa3b, v141
	v_exp_f32_e32 v141, v141
	v_mul_f32_e32 v162, 0xbfb8aa3b, v162
	v_exp_f32_e32 v162, v162
	v_add_f32_e32 v140, 1.0, v140
	v_min_f32_e32 v167, 0x60ad78ec, v141
	v_lshlrev_b32_e32 v141, 16, v165
	v_add_f32_e32 v141, v138, v141
	v_mul_f32_e32 v141, 0xbfb8aa3b, v141
	v_rcp_f32_e32 v168, v140
	v_min_f32_e32 v140, 0x60ad78ec, v162
	v_exp_f32_e32 v141, v141
	v_lshlrev_b32_e32 v162, 16, v163
	v_add_f32_e32 v162, v134, v162
	v_mul_f32_e32 v162, 0xbfb8aa3b, v162
	v_and_b32_e32 v163, 0xffff0000, v163
	v_exp_f32_e32 v164, v162
	v_add_f32_e32 v163, v135, v163
	v_min_f32_e32 v162, 0x60ad78ec, v141
	v_and_b32_e32 v141, 0xffff0000, v165
	v_mul_f32_e32 v163, 0xbfb8aa3b, v163
	v_add_f32_e32 v141, v139, v141
	v_exp_f32_e32 v165, v163
	v_add_f32_e32 v140, 1.0, v140
	v_mul_f32_e32 v141, 0xbfb8aa3b, v141
	v_rcp_f32_e32 v169, v140
	v_min_f32_e32 v140, 0x60ad78ec, v164
	v_exp_f32_e32 v141, v141
	v_add_f32_e32 v140, 1.0, v140
	v_rcp_f32_e32 v164, v140
	v_min_f32_e32 v140, 0x60ad78ec, v165
	v_add_f32_e32 v140, 1.0, v140
	v_min_f32_e32 v163, 0x60ad78ec, v141
	v_rcp_f32_e32 v165, v140
	s_waitcnt vmcnt(4)
	v_lshlrev_b32_e32 v140, 16, v160
	v_lshlrev_b32_e32 v141, 16, v158
	v_add_f32_e32 v140, v136, v140
	v_add_f32_e32 v141, v132, v141
	v_mul_f32_e32 v140, 0xbfb8aa3b, v140
	v_mul_f32_e32 v141, 0xbfb8aa3b, v141
	v_exp_f32_e32 v140, v140
	v_exp_f32_e32 v141, v141
	v_pk_add_f32 v[162:163], v[162:163], 1.0 op_sel_hi:[1,0]
	v_and_b32_e32 v158, 0xffff0000, v158
	v_pk_mul_f32 v[162:163], v[162:163], v[164:165]
	v_add_f32_e32 v158, v133, v158
	v_pk_mul_f32 v[58:59], v[58:59], v[162:163]
	v_min_f32_e32 v162, 0x60ad78ec, v140
	v_min_f32_e32 v140, 0x60ad78ec, v141
	v_and_b32_e32 v141, 0xffff0000, v160
	v_add_f32_e32 v141, v137, v141
	v_mul_f32_e32 v141, 0xbfb8aa3b, v141
	v_exp_f32_e32 v141, v141
	v_mul_f32_e32 v158, 0xbfb8aa3b, v158
	v_exp_f32_e32 v158, v158
	v_add_f32_e32 v140, 1.0, v140
	v_min_f32_e32 v163, 0x60ad78ec, v141
	v_lshlrev_b32_e32 v141, 16, v161
	v_add_f32_e32 v141, v138, v141
	v_mul_f32_e32 v141, 0xbfb8aa3b, v141
	v_rcp_f32_e32 v164, v140
	v_min_f32_e32 v140, 0x60ad78ec, v158
	v_exp_f32_e32 v141, v141
	v_lshlrev_b32_e32 v158, 16, v159
	v_add_f32_e32 v158, v134, v158
	v_mul_f32_e32 v158, 0xbfb8aa3b, v158
	v_and_b32_e32 v159, 0xffff0000, v159
	v_exp_f32_e32 v160, v158
	v_add_f32_e32 v159, v135, v159
	v_min_f32_e32 v158, 0x60ad78ec, v141
	v_and_b32_e32 v141, 0xffff0000, v161
	v_mul_f32_e32 v159, 0xbfb8aa3b, v159
	v_add_f32_e32 v141, v139, v141
	v_exp_f32_e32 v161, v159
	v_add_f32_e32 v140, 1.0, v140
	v_mul_f32_e32 v141, 0xbfb8aa3b, v141
	v_rcp_f32_e32 v165, v140
	v_min_f32_e32 v140, 0x60ad78ec, v160
	v_exp_f32_e32 v141, v141
	v_add_f32_e32 v140, 1.0, v140
	v_rcp_f32_e32 v160, v140
	v_min_f32_e32 v140, 0x60ad78ec, v161
	v_add_f32_e32 v140, 1.0, v140
	v_min_f32_e32 v159, 0x60ad78ec, v141
	v_rcp_f32_e32 v161, v140
	s_waitcnt vmcnt(2)
	v_lshlrev_b32_e32 v140, 16, v156
	v_lshlrev_b32_e32 v141, 16, v154
	v_add_f32_e32 v140, v136, v140
	v_add_f32_e32 v141, v132, v141
	v_mul_f32_e32 v140, 0xbfb8aa3b, v140
	v_mul_f32_e32 v141, 0xbfb8aa3b, v141
	v_exp_f32_e32 v140, v140
	v_exp_f32_e32 v141, v141
	v_pk_add_f32 v[158:159], v[158:159], 1.0 op_sel_hi:[1,0]
	v_and_b32_e32 v154, 0xffff0000, v154
	v_pk_mul_f32 v[158:159], v[158:159], v[160:161]
	v_add_f32_e32 v154, v133, v154
	v_pk_mul_f32 v[42:43], v[42:43], v[158:159]
	v_min_f32_e32 v158, 0x60ad78ec, v140
	v_min_f32_e32 v140, 0x60ad78ec, v141
	v_and_b32_e32 v141, 0xffff0000, v156
	v_add_f32_e32 v141, v137, v141
	v_mul_f32_e32 v141, 0xbfb8aa3b, v141
	v_exp_f32_e32 v141, v141
	v_mul_f32_e32 v154, 0xbfb8aa3b, v154
	v_exp_f32_e32 v154, v154
	v_add_f32_e32 v140, 1.0, v140
	v_min_f32_e32 v159, 0x60ad78ec, v141
	v_lshlrev_b32_e32 v141, 16, v157
	v_add_f32_e32 v141, v138, v141
	v_rcp_f32_e32 v160, v140
	v_min_f32_e32 v140, 0x60ad78ec, v154
	v_mul_f32_e32 v141, 0xbfb8aa3b, v141
	v_lshlrev_b32_e32 v154, 16, v155
	v_exp_f32_e32 v141, v141
	v_add_f32_e32 v154, v134, v154
	v_mul_f32_e32 v154, 0xbfb8aa3b, v154
	v_and_b32_e32 v155, 0xffff0000, v155
	v_exp_f32_e32 v156, v154
	v_add_f32_e32 v155, v135, v155
	v_mul_f32_e32 v155, 0xbfb8aa3b, v155
	v_min_f32_e32 v154, 0x60ad78ec, v141
	v_and_b32_e32 v141, 0xffff0000, v157
	v_exp_f32_e32 v157, v155
	v_add_f32_e32 v140, 1.0, v140
	v_rcp_f32_e32 v161, v140
	v_min_f32_e32 v140, 0x60ad78ec, v156
	v_add_f32_e32 v140, 1.0, v140
	v_rcp_f32_e32 v156, v140
	v_min_f32_e32 v140, 0x60ad78ec, v157
	v_add_f32_e32 v140, 1.0, v140
	v_rcp_f32_e32 v157, v140
	s_waitcnt vmcnt(0)
	v_lshlrev_b32_e32 v140, 16, v152
	v_add_f32_e32 v136, v136, v140
	v_lshlrev_b32_e32 v140, 16, v2
	v_add_f32_e32 v132, v132, v140
	v_mul_f32_e32 v136, 0xbfb8aa3b, v136
	v_mul_f32_e32 v132, 0xbfb8aa3b, v132
	v_exp_f32_e32 v136, v136
	v_exp_f32_e32 v140, v132
	v_and_b32_e32 v2, 0xffff0000, v2
	v_add_f32_e32 v2, v133, v2
	v_min_f32_e32 v132, 0x60ad78ec, v136
	v_min_f32_e32 v136, 0x60ad78ec, v140
	v_and_b32_e32 v140, 0xffff0000, v152
	v_add_f32_e32 v137, v137, v140
	v_mul_f32_e32 v137, 0xbfb8aa3b, v137
	v_exp_f32_e32 v137, v137
	v_add_f32_e32 v133, 1.0, v136
	v_mul_f32_e32 v2, 0xbfb8aa3b, v2
	v_rcp_f32_e32 v136, v133
	v_min_f32_e32 v133, 0x60ad78ec, v137
	v_lshlrev_b32_e32 v137, 16, v153
	v_exp_f32_e32 v2, v2
	v_add_f32_e32 v137, v138, v137
	v_mul_f32_e32 v137, 0xbfb8aa3b, v137
	v_exp_f32_e32 v138, v137
	v_lshlrev_b32_e32 v137, 16, v3
	v_and_b32_e32 v3, 0xffff0000, v3
	v_add_f32_e32 v134, v134, v137
	v_add_f32_e32 v3, v135, v3
	v_min_f32_e32 v2, 0x60ad78ec, v2
	v_mul_f32_e32 v134, 0xbfb8aa3b, v134
	v_mul_f32_e32 v3, 0xbfb8aa3b, v3
	v_exp_f32_e32 v134, v134
	v_add_f32_e32 v2, 1.0, v2
	v_exp_f32_e32 v135, v3
	v_rcp_f32_e32 v137, v2
	v_min_f32_e32 v2, 0x60ad78ec, v138
	v_and_b32_e32 v138, 0xffff0000, v153
	v_add_f32_e32 v138, v139, v138
	v_mul_f32_e32 v138, 0xbfb8aa3b, v138
	v_min_f32_e32 v134, 0x60ad78ec, v134
	v_exp_f32_e32 v138, v138
	v_min_f32_e32 v135, 0x60ad78ec, v135
	v_add_f32_e32 v141, v139, v141
	v_add_f32_e32 v3, 1.0, v134
	v_add_f32_e32 v135, 1.0, v135
	v_mul_f32_e32 v141, 0xbfb8aa3b, v141
	v_rcp_f32_e32 v134, v3
	v_rcp_f32_e32 v135, v135
	v_exp_f32_e32 v141, v141
	v_min_f32_e32 v3, 0x60ad78ec, v138
	v_pk_add_f32 v[2:3], v[2:3], 1.0 op_sel_hi:[1,0]
	v_pk_add_f32 v[132:133], v[132:133], 1.0 op_sel_hi:[1,0]
	v_pk_mul_f32 v[2:3], v[2:3], v[134:135]
	v_min_f32_e32 v155, 0x60ad78ec, v141
	v_pk_mul_f32 v[10:11], v[10:11], v[2:3]
	v_add_u32_e32 v2, s83, v0
	v_pk_add_f32 v[154:155], v[154:155], 1.0 op_sel_hi:[1,0]
	v_ashrrev_i32_e32 v3, 31, v2
	v_pk_mul_f32 v[154:155], v[154:155], v[156:157]
	v_pk_mul_f32 v[152:153], v[132:133], v[136:137]
	v_lshl_add_u64 v[136:137], v[2:3], 2, s[6:7]
	v_lshlrev_b64 v[2:3], 1, v[2:3]
	v_pk_mul_f32 v[26:27], v[26:27], v[154:155]
	v_mad_i64_i32 v[154:155], vcc, v174, s2, v[2:3]
	v_lshl_add_u64 v[154:155], s[30:31], 0, v[154:155]
	v_add_co_u32_e32 v156, vcc, s76, v154
	v_pk_add_f32 v[182:183], v[182:183], 1.0 op_sel_hi:[1,0]
	s_nop 0
	v_addc_co_u32_e32 v157, vcc, 0, v155, vcc
	v_add_co_u32_e32 v154, vcc, s77, v154
	v_pk_mul_f32 v[182:183], v[182:183], v[184:185]
	s_nop 0
	v_addc_co_u32_e32 v155, vcc, 0, v155, vcc
	v_pk_mul_f32 v[88:89], v[88:89], v[182:183]
	v_pk_add_f32 v[158:159], v[158:159], 1.0 op_sel_hi:[1,0]
	global_load_dwordx4 v[132:135], v[136:137], off offset:-4096
	s_nop 0
	global_load_dwordx4 v[136:139], v[136:137], off
	v_pk_mul_f32 v[158:159], v[158:159], v[160:161]
	global_load_dwordx2 v[182:183], v[154:155], off offset:1024
	v_mad_i64_i32 v[154:155], vcc, v175, s2, v[2:3]
	v_lshl_add_u64 v[154:155], s[30:31], 0, v[154:155]
	v_pk_mul_f32 v[24:25], v[24:25], v[158:159]
	v_add_co_u32_e32 v158, vcc, s76, v154
	v_pk_mul_f32 v[8:9], v[8:9], v[152:153]
	s_nop 0
	v_addc_co_u32_e32 v159, vcc, 0, v155, vcc
	v_add_co_u32_e32 v154, vcc, s77, v154
	v_pk_add_f32 v[170:171], v[170:171], 1.0 op_sel_hi:[1,0]
	s_nop 0
	v_addc_co_u32_e32 v155, vcc, 0, v155, vcc
	global_load_dwordx2 v[174:175], v[158:159], off offset:3072
	global_load_dwordx2 v[184:185], v[154:155], off offset:1024
	global_load_dwordx2 v[186:187], v[156:157], off offset:3072
	v_mad_i64_i32 v[152:153], vcc, v176, s2, v[2:3]
	v_lshl_add_u64 v[152:153], s[30:31], 0, v[152:153]
	v_add_co_u32_e32 v154, vcc, s76, v152
	v_pk_add_f32 v[166:167], v[166:167], 1.0 op_sel_hi:[1,0]
	s_nop 0
	v_addc_co_u32_e32 v155, vcc, 0, v153, vcc
	v_add_co_u32_e32 v152, vcc, s77, v152
	v_pk_mul_f32 v[170:171], v[170:171], v[172:173]
	s_nop 0
	v_addc_co_u32_e32 v153, vcc, 0, v153, vcc
	v_mad_i64_i32 v[156:157], vcc, v177, s2, v[2:3]
	v_lshl_add_u64 v[156:157], s[30:31], 0, v[156:157]
	v_add_co_u32_e32 v158, vcc, s76, v156
	v_pk_mul_f32 v[166:167], v[166:167], v[168:169]
	s_nop 0
	v_addc_co_u32_e32 v159, vcc, 0, v157, vcc
	v_add_co_u32_e32 v156, vcc, s77, v156
	v_pk_mul_f32 v[72:73], v[72:73], v[170:171]
	v_pk_mul_f32 v[56:57], v[56:57], v[166:167]
	v_addc_co_u32_e32 v157, vcc, 0, v157, vcc
	global_load_dwordx2 v[170:171], v[154:155], off offset:3072
	global_load_dwordx2 v[172:173], v[152:153], off offset:1024
	global_load_dwordx2 v[166:167], v[158:159], off offset:3072
	global_load_dwordx2 v[168:169], v[156:157], off offset:1024
	v_mad_i64_i32 v[152:153], vcc, v178, s2, v[2:3]
	v_lshl_add_u64 v[152:153], s[30:31], 0, v[152:153]
	v_add_co_u32_e32 v154, vcc, s76, v152
	v_pk_add_f32 v[162:163], v[162:163], 1.0 op_sel_hi:[1,0]
	s_nop 0
	v_addc_co_u32_e32 v155, vcc, 0, v153, vcc
	v_add_co_u32_e32 v152, vcc, s77, v152
	v_pk_mul_f32 v[162:163], v[162:163], v[164:165]
	s_nop 0
	v_addc_co_u32_e32 v153, vcc, 0, v153, vcc
	v_mad_i64_i32 v[156:157], vcc, v179, s2, v[2:3]
	v_lshl_add_u64 v[156:157], s[30:31], 0, v[156:157]
	v_add_co_u32_e32 v158, vcc, s76, v156
	v_pk_mul_f32 v[40:41], v[40:41], v[162:163]
	s_nop 0
	v_addc_co_u32_e32 v159, vcc, 0, v157, vcc
	v_add_co_u32_e32 v156, vcc, s77, v156
	v_pk_mul_f32 v[120:121], v[120:121], v[190:191]
	s_nop 0
	v_addc_co_u32_e32 v157, vcc, 0, v157, vcc
	global_load_dwordx2 v[162:163], v[154:155], off offset:3072
	global_load_dwordx2 v[164:165], v[152:153], off offset:1024
	s_nop 0
	global_load_dwordx2 v[158:159], v[158:159], off offset:3072
	s_nop 0
	global_load_dwordx2 v[160:161], v[156:157], off offset:1024
	v_mad_i64_i32 v[152:153], vcc, v180, s2, v[2:3]
	v_lshl_add_u64 v[152:153], s[30:31], 0, v[152:153]
	v_add_co_u32_e32 v154, vcc, s76, v152
	s_waitcnt vmcnt(11)
	v_lshlrev_b32_e32 v0, 16, v182
	v_addc_co_u32_e32 v155, vcc, 0, v153, vcc
	v_add_co_u32_e32 v152, vcc, s77, v152
	v_add_f32_e32 v0, v136, v0
	s_nop 0
	v_addc_co_u32_e32 v153, vcc, 0, v153, vcc
	v_mad_i64_i32 v[2:3], vcc, v181, s2, v[2:3]
	v_lshl_add_u64 v[2:3], s[30:31], 0, v[2:3]
	v_add_co_u32_e32 v176, vcc, s76, v2
	v_mul_f32_e32 v0, 0xbfb8aa3b, v0
	s_nop 0
	v_addc_co_u32_e32 v177, vcc, 0, v3, vcc
	v_add_co_u32_e32 v178, vcc, s77, v2
	s_waitcnt vmcnt(8)
	v_lshlrev_b32_e32 v2, 16, v186
	v_add_f32_e32 v2, v132, v2
	v_mul_f32_e32 v2, 0xbfb8aa3b, v2
	v_exp_f32_e32 v0, v0
	v_exp_f32_e32 v140, v2
	v_and_b32_e32 v141, 0xffff0000, v186
	v_add_f32_e32 v141, v133, v141
	v_addc_co_u32_e32 v179, vcc, 0, v3, vcc
	global_load_dwordx2 v[154:155], v[154:155], off offset:3072
	s_nop 0
	global_load_dwordx2 v[156:157], v[152:153], off offset:1024
	global_load_dwordx2 v[2:3], v[176:177], off offset:3072
	s_nop 0
	global_load_dwordx2 v[152:153], v[178:179], off offset:1024
	v_min_f32_e32 v176, 0x60ad78ec, v0
	v_min_f32_e32 v0, 0x60ad78ec, v140
	v_and_b32_e32 v140, 0xffff0000, v182
	v_mul_f32_e32 v141, 0xbfb8aa3b, v141
	v_add_f32_e32 v140, v137, v140
	v_exp_f32_e32 v141, v141
	v_mul_f32_e32 v140, 0xbfb8aa3b, v140
	v_exp_f32_e32 v140, v140
	v_add_f32_e32 v0, 1.0, v0
	v_rcp_f32_e32 v178, v0
	v_min_f32_e32 v0, 0x60ad78ec, v141
	v_lshlrev_b32_e32 v141, 16, v187
	v_add_f32_e32 v141, v134, v141
	v_min_f32_e32 v177, 0x60ad78ec, v140
	v_lshlrev_b32_e32 v140, 16, v183
	v_mul_f32_e32 v141, 0xbfb8aa3b, v141
	v_add_f32_e32 v140, v138, v140
	v_exp_f32_e32 v141, v141
	v_mul_f32_e32 v140, 0xbfb8aa3b, v140
	v_exp_f32_e32 v140, v140
	v_add_f32_e32 v0, 1.0, v0
	v_rcp_f32_e32 v179, v0
	v_min_f32_e32 v0, 0x60ad78ec, v141
	v_and_b32_e32 v141, 0xffff0000, v187
	v_add_f32_e32 v141, v135, v141
	v_min_f32_e32 v180, 0x60ad78ec, v140
	v_and_b32_e32 v140, 0xffff0000, v183
	v_mul_f32_e32 v141, 0xbfb8aa3b, v141
	v_add_f32_e32 v140, v139, v140
	v_exp_f32_e32 v141, v141
	v_mul_f32_e32 v140, 0xbfb8aa3b, v140
	v_exp_f32_e32 v140, v140
	v_add_f32_e32 v0, 1.0, v0
	v_rcp_f32_e32 v182, v0
	v_min_f32_e32 v0, 0x60ad78ec, v141
	v_add_f32_e32 v0, 1.0, v0
	v_min_f32_e32 v181, 0x60ad78ec, v140
	v_rcp_f32_e32 v183, v0
	v_lshlrev_b32_e32 v0, 16, v184
	v_lshlrev_b32_e32 v140, 16, v174
	v_add_f32_e32 v0, v136, v0
	v_add_f32_e32 v140, v132, v140
	v_mul_f32_e32 v0, 0xbfb8aa3b, v0
	v_mul_f32_e32 v140, 0xbfb8aa3b, v140
	v_exp_f32_e32 v0, v0
	v_exp_f32_e32 v140, v140
	v_pk_add_f32 v[176:177], v[176:177], 1.0 op_sel_hi:[1,0]
	v_and_b32_e32 v141, 0xffff0000, v174
	v_pk_mul_f32 v[176:177], v[176:177], v[178:179]
	v_add_f32_e32 v141, v133, v141
	v_pk_mul_f32 v[116:117], v[116:117], v[176:177]
	v_min_f32_e32 v176, 0x60ad78ec, v0
	v_min_f32_e32 v0, 0x60ad78ec, v140
	v_and_b32_e32 v140, 0xffff0000, v184
	v_mul_f32_e32 v141, 0xbfb8aa3b, v141
	v_add_f32_e32 v140, v137, v140
	v_exp_f32_e32 v141, v141
	v_mul_f32_e32 v140, 0xbfb8aa3b, v140
	v_pk_add_f32 v[180:181], v[180:181], 1.0 op_sel_hi:[1,0]
	v_exp_f32_e32 v140, v140
	v_pk_mul_f32 v[178:179], v[180:181], v[182:183]
	v_add_f32_e32 v0, 1.0, v0
	v_pk_mul_f32 v[118:119], v[118:119], v[178:179]
	v_rcp_f32_e32 v178, v0
	v_min_f32_e32 v0, 0x60ad78ec, v141
	v_lshlrev_b32_e32 v141, 16, v175
	v_add_f32_e32 v141, v134, v141
	v_min_f32_e32 v177, 0x60ad78ec, v140
	v_lshlrev_b32_e32 v140, 16, v185
	v_mul_f32_e32 v141, 0xbfb8aa3b, v141
	v_add_f32_e32 v140, v138, v140
	v_exp_f32_e32 v141, v141
	v_mul_f32_e32 v140, 0xbfb8aa3b, v140
	v_exp_f32_e32 v140, v140
	v_add_f32_e32 v0, 1.0, v0
	v_rcp_f32_e32 v179, v0
	v_min_f32_e32 v0, 0x60ad78ec, v141
	v_and_b32_e32 v141, 0xffff0000, v175
	v_add_f32_e32 v141, v135, v141
	v_min_f32_e32 v174, 0x60ad78ec, v140
	v_and_b32_e32 v140, 0xffff0000, v185
	v_mul_f32_e32 v141, 0xbfb8aa3b, v141
	v_add_f32_e32 v140, v139, v140
	v_exp_f32_e32 v141, v141
	v_mul_f32_e32 v140, 0xbfb8aa3b, v140
	v_exp_f32_e32 v140, v140
	v_add_f32_e32 v0, 1.0, v0
	v_rcp_f32_e32 v180, v0
	v_min_f32_e32 v0, 0x60ad78ec, v141
	v_add_f32_e32 v0, 1.0, v0
	v_min_f32_e32 v175, 0x60ad78ec, v140
	v_rcp_f32_e32 v181, v0
	s_waitcnt vmcnt(10)
	v_lshlrev_b32_e32 v0, 16, v172
	v_lshlrev_b32_e32 v140, 16, v170
	v_add_f32_e32 v0, v136, v0
	v_add_f32_e32 v140, v132, v140
	v_mul_f32_e32 v0, 0xbfb8aa3b, v0
	v_mul_f32_e32 v140, 0xbfb8aa3b, v140
	v_exp_f32_e32 v0, v0
	v_exp_f32_e32 v140, v140
	v_pk_add_f32 v[174:175], v[174:175], 1.0 op_sel_hi:[1,0]
	v_and_b32_e32 v141, 0xffff0000, v170
	v_pk_mul_f32 v[174:175], v[174:175], v[180:181]
	v_add_f32_e32 v141, v133, v141
	v_pk_mul_f32 v[102:103], v[102:103], v[174:175]
	v_min_f32_e32 v174, 0x60ad78ec, v0
	v_min_f32_e32 v0, 0x60ad78ec, v140
	v_and_b32_e32 v140, 0xffff0000, v172
	v_mul_f32_e32 v141, 0xbfb8aa3b, v141
	v_add_f32_e32 v140, v137, v140
	v_exp_f32_e32 v141, v141
	v_mul_f32_e32 v140, 0xbfb8aa3b, v140
	v_pk_add_f32 v[176:177], v[176:177], 1.0 op_sel_hi:[1,0]
	v_exp_f32_e32 v140, v140
	v_pk_mul_f32 v[176:177], v[176:177], v[178:179]
	v_add_f32_e32 v0, 1.0, v0
	v_pk_mul_f32 v[100:101], v[100:101], v[176:177]
	v_rcp_f32_e32 v176, v0
	v_min_f32_e32 v0, 0x60ad78ec, v141
	v_lshlrev_b32_e32 v141, 16, v171
	v_add_f32_e32 v141, v134, v141
	v_min_f32_e32 v175, 0x60ad78ec, v140
	v_lshlrev_b32_e32 v140, 16, v173
	v_mul_f32_e32 v141, 0xbfb8aa3b, v141
	v_add_f32_e32 v140, v138, v140
	v_exp_f32_e32 v141, v141
	v_mul_f32_e32 v140, 0xbfb8aa3b, v140
	v_exp_f32_e32 v140, v140
	v_add_f32_e32 v0, 1.0, v0
	v_rcp_f32_e32 v177, v0
	v_min_f32_e32 v0, 0x60ad78ec, v141
	v_and_b32_e32 v141, 0xffff0000, v171
	v_add_f32_e32 v141, v135, v141
	v_min_f32_e32 v170, 0x60ad78ec, v140
	v_and_b32_e32 v140, 0xffff0000, v173
	v_mul_f32_e32 v141, 0xbfb8aa3b, v141
	v_add_f32_e32 v140, v139, v140
	v_exp_f32_e32 v141, v141
	v_mul_f32_e32 v140, 0xbfb8aa3b, v140
	v_exp_f32_e32 v140, v140
	v_add_f32_e32 v0, 1.0, v0
	v_rcp_f32_e32 v172, v0
	v_min_f32_e32 v0, 0x60ad78ec, v141
	v_add_f32_e32 v0, 1.0, v0
	v_min_f32_e32 v171, 0x60ad78ec, v140
	v_rcp_f32_e32 v173, v0
	s_waitcnt vmcnt(8)
	v_lshlrev_b32_e32 v0, 16, v168
	v_lshlrev_b32_e32 v140, 16, v166
	v_add_f32_e32 v0, v136, v0
	v_add_f32_e32 v140, v132, v140
	v_mul_f32_e32 v0, 0xbfb8aa3b, v0
	v_mul_f32_e32 v140, 0xbfb8aa3b, v140
	v_exp_f32_e32 v0, v0
	v_exp_f32_e32 v140, v140
	v_pk_add_f32 v[170:171], v[170:171], 1.0 op_sel_hi:[1,0]
	v_and_b32_e32 v141, 0xffff0000, v166
	v_pk_mul_f32 v[170:171], v[170:171], v[172:173]
	v_add_f32_e32 v141, v133, v141
	v_pk_mul_f32 v[86:87], v[86:87], v[170:171]
	v_min_f32_e32 v170, 0x60ad78ec, v0
	v_min_f32_e32 v0, 0x60ad78ec, v140
	v_and_b32_e32 v140, 0xffff0000, v168
	v_mul_f32_e32 v141, 0xbfb8aa3b, v141
	v_add_f32_e32 v140, v137, v140
	v_exp_f32_e32 v141, v141
	v_mul_f32_e32 v140, 0xbfb8aa3b, v140
	v_exp_f32_e32 v140, v140
	v_add_f32_e32 v0, 1.0, v0
	v_rcp_f32_e32 v172, v0
	v_min_f32_e32 v0, 0x60ad78ec, v141
	v_lshlrev_b32_e32 v141, 16, v167
	v_add_f32_e32 v141, v134, v141
	v_min_f32_e32 v171, 0x60ad78ec, v140
	v_lshlrev_b32_e32 v140, 16, v169
	v_mul_f32_e32 v141, 0xbfb8aa3b, v141
	v_add_f32_e32 v140, v138, v140
	v_exp_f32_e32 v141, v141
	v_mul_f32_e32 v140, 0xbfb8aa3b, v140
	v_exp_f32_e32 v140, v140
	v_add_f32_e32 v0, 1.0, v0
	v_rcp_f32_e32 v173, v0
	v_min_f32_e32 v0, 0x60ad78ec, v141
	v_and_b32_e32 v141, 0xffff0000, v167
	v_add_f32_e32 v141, v135, v141
	v_min_f32_e32 v166, 0x60ad78ec, v140
	v_and_b32_e32 v140, 0xffff0000, v169
	v_mul_f32_e32 v141, 0xbfb8aa3b, v141
	v_add_f32_e32 v140, v139, v140
	v_exp_f32_e32 v141, v141
	v_mul_f32_e32 v140, 0xbfb8aa3b, v140
	v_exp_f32_e32 v140, v140
	v_add_f32_e32 v0, 1.0, v0
	v_rcp_f32_e32 v168, v0
	v_min_f32_e32 v0, 0x60ad78ec, v141
	v_add_f32_e32 v0, 1.0, v0
	v_min_f32_e32 v167, 0x60ad78ec, v140
	v_rcp_f32_e32 v169, v0
	s_waitcnt vmcnt(6)
	v_lshlrev_b32_e32 v0, 16, v164
	v_lshlrev_b32_e32 v140, 16, v162
	v_add_f32_e32 v0, v136, v0
	v_add_f32_e32 v140, v132, v140
	v_mul_f32_e32 v0, 0xbfb8aa3b, v0
	v_mul_f32_e32 v140, 0xbfb8aa3b, v140
	v_exp_f32_e32 v0, v0
	v_exp_f32_e32 v140, v140
	v_pk_add_f32 v[166:167], v[166:167], 1.0 op_sel_hi:[1,0]
	v_and_b32_e32 v141, 0xffff0000, v162
	v_pk_mul_f32 v[166:167], v[166:167], v[168:169]
	v_add_f32_e32 v141, v133, v141
	v_pk_mul_f32 v[70:71], v[70:71], v[166:167]
	v_min_f32_e32 v166, 0x60ad78ec, v0
	v_min_f32_e32 v0, 0x60ad78ec, v140
	v_and_b32_e32 v140, 0xffff0000, v164
	v_mul_f32_e32 v141, 0xbfb8aa3b, v141
	v_add_f32_e32 v140, v137, v140
	v_exp_f32_e32 v141, v141
	v_mul_f32_e32 v140, 0xbfb8aa3b, v140
	v_exp_f32_e32 v140, v140
	v_add_f32_e32 v0, 1.0, v0
	v_rcp_f32_e32 v168, v0
	v_min_f32_e32 v0, 0x60ad78ec, v141
	v_lshlrev_b32_e32 v141, 16, v163
	v_add_f32_e32 v141, v134, v141
	v_min_f32_e32 v167, 0x60ad78ec, v140
	v_lshlrev_b32_e32 v140, 16, v165
	v_mul_f32_e32 v141, 0xbfb8aa3b, v141
	v_add_f32_e32 v140, v138, v140
	v_exp_f32_e32 v141, v141
	v_mul_f32_e32 v140, 0xbfb8aa3b, v140
	v_exp_f32_e32 v140, v140
	v_add_f32_e32 v0, 1.0, v0
	v_rcp_f32_e32 v169, v0
	v_min_f32_e32 v0, 0x60ad78ec, v141
	v_and_b32_e32 v141, 0xffff0000, v163
	v_add_f32_e32 v141, v135, v141
	v_min_f32_e32 v162, 0x60ad78ec, v140
	v_and_b32_e32 v140, 0xffff0000, v165
	v_mul_f32_e32 v141, 0xbfb8aa3b, v141
	v_add_f32_e32 v140, v139, v140
	v_exp_f32_e32 v141, v141
	v_mul_f32_e32 v140, 0xbfb8aa3b, v140
	v_exp_f32_e32 v140, v140
	v_add_f32_e32 v0, 1.0, v0
	v_rcp_f32_e32 v164, v0
	v_min_f32_e32 v0, 0x60ad78ec, v141
	v_add_f32_e32 v0, 1.0, v0
	v_min_f32_e32 v163, 0x60ad78ec, v140
	v_rcp_f32_e32 v165, v0
	s_waitcnt vmcnt(4)
	v_lshlrev_b32_e32 v0, 16, v160
	v_lshlrev_b32_e32 v140, 16, v158
	v_add_f32_e32 v0, v136, v0
	v_add_f32_e32 v140, v132, v140
	v_mul_f32_e32 v0, 0xbfb8aa3b, v0
	v_mul_f32_e32 v140, 0xbfb8aa3b, v140
	v_exp_f32_e32 v0, v0
	v_exp_f32_e32 v140, v140
	v_pk_add_f32 v[162:163], v[162:163], 1.0 op_sel_hi:[1,0]
	v_and_b32_e32 v141, 0xffff0000, v158
	v_pk_mul_f32 v[162:163], v[162:163], v[164:165]
	v_add_f32_e32 v141, v133, v141
	v_pk_mul_f32 v[54:55], v[54:55], v[162:163]
	v_min_f32_e32 v162, 0x60ad78ec, v0
	v_min_f32_e32 v0, 0x60ad78ec, v140
	v_and_b32_e32 v140, 0xffff0000, v160
	v_mul_f32_e32 v141, 0xbfb8aa3b, v141
	v_add_f32_e32 v140, v137, v140
	v_exp_f32_e32 v141, v141
	v_mul_f32_e32 v140, 0xbfb8aa3b, v140
	v_exp_f32_e32 v140, v140
	v_add_f32_e32 v0, 1.0, v0
	v_rcp_f32_e32 v164, v0
	v_min_f32_e32 v0, 0x60ad78ec, v141
	v_lshlrev_b32_e32 v141, 16, v159
	v_add_f32_e32 v141, v134, v141
	v_min_f32_e32 v163, 0x60ad78ec, v140
	v_lshlrev_b32_e32 v140, 16, v161
	v_mul_f32_e32 v141, 0xbfb8aa3b, v141
	v_add_f32_e32 v140, v138, v140
	v_exp_f32_e32 v141, v141
	v_mul_f32_e32 v140, 0xbfb8aa3b, v140
	v_exp_f32_e32 v140, v140
	v_add_f32_e32 v0, 1.0, v0
	v_rcp_f32_e32 v165, v0
	v_min_f32_e32 v0, 0x60ad78ec, v141
	v_and_b32_e32 v141, 0xffff0000, v159
	v_add_f32_e32 v141, v135, v141
	v_min_f32_e32 v158, 0x60ad78ec, v140
	v_and_b32_e32 v140, 0xffff0000, v161
	v_mul_f32_e32 v141, 0xbfb8aa3b, v141
	v_add_f32_e32 v140, v139, v140
	v_exp_f32_e32 v141, v141
	v_mul_f32_e32 v140, 0xbfb8aa3b, v140
	v_exp_f32_e32 v140, v140
	v_add_f32_e32 v0, 1.0, v0
	v_rcp_f32_e32 v160, v0
	v_min_f32_e32 v0, 0x60ad78ec, v141
	v_add_f32_e32 v0, 1.0, v0
	v_min_f32_e32 v159, 0x60ad78ec, v140
	v_rcp_f32_e32 v161, v0
	s_waitcnt vmcnt(2)
	v_lshlrev_b32_e32 v0, 16, v156
	v_lshlrev_b32_e32 v140, 16, v154
	v_add_f32_e32 v0, v136, v0
	v_add_f32_e32 v140, v132, v140
	v_mul_f32_e32 v0, 0xbfb8aa3b, v0
	v_mul_f32_e32 v140, 0xbfb8aa3b, v140
	v_and_b32_e32 v141, 0xffff0000, v154
	v_exp_f32_e32 v0, v0
	v_exp_f32_e32 v140, v140
	v_add_f32_e32 v141, v133, v141
	v_mul_f32_e32 v141, 0xbfb8aa3b, v141
	v_pk_add_f32 v[158:159], v[158:159], 1.0 op_sel_hi:[1,0]
	v_exp_f32_e32 v141, v141
	v_pk_mul_f32 v[158:159], v[158:159], v[160:161]
	v_pk_add_f32 v[174:175], v[174:175], 1.0 op_sel_hi:[1,0]
	v_pk_mul_f32 v[38:39], v[38:39], v[158:159]
	v_min_f32_e32 v158, 0x60ad78ec, v0
	v_min_f32_e32 v0, 0x60ad78ec, v140
	v_add_f32_e32 v0, 1.0, v0
	v_rcp_f32_e32 v160, v0
	v_min_f32_e32 v0, 0x60ad78ec, v141
	v_lshlrev_b32_e32 v141, 16, v155
	v_add_f32_e32 v141, v134, v141
	v_and_b32_e32 v140, 0xffff0000, v156
	v_mul_f32_e32 v141, 0xbfb8aa3b, v141
	v_add_f32_e32 v140, v137, v140
	v_exp_f32_e32 v141, v141
	v_mul_f32_e32 v140, 0xbfb8aa3b, v140
	v_exp_f32_e32 v140, v140
	v_add_f32_e32 v0, 1.0, v0
	v_rcp_f32_e32 v161, v0
	v_min_f32_e32 v0, 0x60ad78ec, v141
	v_and_b32_e32 v141, 0xffff0000, v155
	v_add_f32_e32 v141, v135, v141
	v_min_f32_e32 v159, 0x60ad78ec, v140
	v_lshlrev_b32_e32 v140, 16, v157
	v_mul_f32_e32 v141, 0xbfb8aa3b, v141
	v_add_f32_e32 v140, v138, v140
	v_exp_f32_e32 v141, v141
	v_mul_f32_e32 v140, 0xbfb8aa3b, v140
	v_exp_f32_e32 v140, v140
	v_add_f32_e32 v0, 1.0, v0
	v_rcp_f32_e32 v156, v0
	v_min_f32_e32 v0, 0x60ad78ec, v141
	v_add_f32_e32 v0, 1.0, v0
	v_min_f32_e32 v154, 0x60ad78ec, v140
	v_and_b32_e32 v140, 0xffff0000, v157
	v_rcp_f32_e32 v157, v0
	s_waitcnt vmcnt(0)
	v_lshlrev_b32_e32 v0, 16, v152
	v_add_f32_e32 v0, v136, v0
	v_lshlrev_b32_e32 v136, 16, v2
	v_add_f32_e32 v132, v132, v136
	v_mul_f32_e32 v0, 0xbfb8aa3b, v0
	v_mul_f32_e32 v132, 0xbfb8aa3b, v132
	v_exp_f32_e32 v0, v0
	v_exp_f32_e32 v136, v132
	v_and_b32_e32 v2, 0xffff0000, v2
	v_add_f32_e32 v2, v133, v2
	v_min_f32_e32 v132, 0x60ad78ec, v0
	v_min_f32_e32 v0, 0x60ad78ec, v136
	v_and_b32_e32 v136, 0xffff0000, v152
	v_add_f32_e32 v136, v137, v136
	v_mul_f32_e32 v136, 0xbfb8aa3b, v136
	v_exp_f32_e32 v137, v136
	v_mul_f32_e32 v2, 0xbfb8aa3b, v2
	v_exp_f32_e32 v2, v2
	v_add_f32_e32 v0, 1.0, v0
	v_min_f32_e32 v133, 0x60ad78ec, v137
	v_lshlrev_b32_e32 v137, 16, v3
	v_add_f32_e32 v134, v134, v137
	v_mul_f32_e32 v134, 0xbfb8aa3b, v134
	v_exp_f32_e32 v134, v134
	v_and_b32_e32 v3, 0xffff0000, v3
	v_add_f32_e32 v3, v135, v3
	v_rcp_f32_e32 v136, v0
	v_min_f32_e32 v0, 0x60ad78ec, v2
	v_mul_f32_e32 v3, 0xbfb8aa3b, v3
	v_add_f32_e32 v0, 1.0, v0
	v_exp_f32_e32 v135, v3
	v_lshlrev_b32_e32 v2, 16, v153
	v_rcp_f32_e32 v137, v0
	v_min_f32_e32 v0, 0x60ad78ec, v134
	v_and_b32_e32 v134, 0xffff0000, v153
	v_add_f32_e32 v140, v139, v140
	v_add_f32_e32 v2, v138, v2
	v_add_f32_e32 v134, v139, v134
	v_mul_f32_e32 v140, 0xbfb8aa3b, v140
	v_mul_f32_e32 v2, 0xbfb8aa3b, v2
	v_mul_f32_e32 v134, 0xbfb8aa3b, v134
	v_add_f32_e32 v0, 1.0, v0
	v_exp_f32_e32 v140, v140
	v_exp_f32_e32 v2, v2
	v_exp_f32_e32 v138, v134
	v_rcp_f32_e32 v134, v0
	v_min_f32_e32 v0, 0x60ad78ec, v135
	v_add_f32_e32 v0, 1.0, v0
	v_rcp_f32_e32 v135, v0
	v_min_f32_e32 v155, 0x60ad78ec, v140
	v_min_f32_e32 v2, 0x60ad78ec, v2
	v_min_f32_e32 v3, 0x60ad78ec, v138
	v_pk_add_f32 v[170:171], v[170:171], 1.0 op_sel_hi:[1,0]
	v_pk_add_f32 v[166:167], v[166:167], 1.0 op_sel_hi:[1,0]
	v_pk_add_f32 v[162:163], v[162:163], 1.0 op_sel_hi:[1,0]
	v_pk_add_f32 v[154:155], v[154:155], 1.0 op_sel_hi:[1,0]
	v_pk_add_f32 v[158:159], v[158:159], 1.0 op_sel_hi:[1,0]
	v_pk_add_f32 v[2:3], v[2:3], 1.0 op_sel_hi:[1,0]
	v_pk_add_f32 v[132:133], v[132:133], 1.0 op_sel_hi:[1,0]
	v_pk_mul_f32 v[174:175], v[174:175], v[176:177]
	v_pk_mul_f32 v[170:171], v[170:171], v[172:173]
	v_pk_mul_f32 v[166:167], v[166:167], v[168:169]
	v_pk_mul_f32 v[162:163], v[162:163], v[164:165]
	v_pk_mul_f32 v[158:159], v[158:159], v[160:161]
	v_pk_mul_f32 v[154:155], v[154:155], v[156:157]
	v_pk_mul_f32 v[132:133], v[132:133], v[136:137]
	v_pk_mul_f32 v[2:3], v[2:3], v[134:135]
	v_pk_mul_f32 v[84:85], v[84:85], v[174:175]
	v_pk_mul_f32 v[68:69], v[68:69], v[170:171]
	v_pk_mul_f32 v[52:53], v[52:53], v[166:167]
	v_pk_mul_f32 v[36:37], v[36:37], v[162:163]
	v_pk_mul_f32 v[22:23], v[22:23], v[154:155]
	v_pk_mul_f32 v[20:21], v[20:21], v[158:159]
	v_pk_mul_f32 v[6:7], v[6:7], v[2:3]
	v_pk_mul_f32 v[4:5], v[4:5], v[132:133]
